# nt on read-once residual loads (P3 x, P6 h1) and write-once final output stores
# speedup vs baseline: 1.0212x; 1.0002x over previous
; DI unsigned cvt_pk(float lo, float hi) { const f32x2 v = {lo, hi}; return __builtin_bit_cast(unsigned, __builtin_convertvector(v, bf16v2)); }
;     __device__ __forceinline__ void operator()(const f32x4 (&acc)[2][2][4][2], const Unit& u, int wr, int wc, int fr, int fq) const {
;         const int col0 = u.pn * 256 + wc * 32 + 8 * fq, rowbase = u.pm * 256 + wr * 64 + fr;
; #pragma unroll
;         for (int ai = 0; ai < 2; ++ai)
; #pragma unroll
;             for (int m = 0; m < 4; ++m) {
;                 const int row = rowbase + ai * 128 + m * 16; const size_t off = (size_t)row * DM + col0;
;                 float q = 0.f;
; #pragma unroll
;                 for (int bj = 0; bj < 2; ++bj) {
;                     const f32x4 r0 = *(const f32x4*)(resid + off + bj * 128), r1 = *(const f32x4*)(resid + off + bj * 128 + 4);
;                     const f32x4 o0 = r0 + acc[ai][bj][m][0], o1 = r1 + acc[ai][bj][m][1];
;                     *(f32x4*)(out + off + bj * 128) = o0; *(f32x4*)(out + off + bj * 128 + 4) = o1;
;                     if (xb) {
;                         u32x4 w; w.x = cvt_pk(o0[0], o0[1]); w.y = cvt_pk(o0[2], o0[3]); w.z = cvt_pk(o1[0], o1[1]); w.w = cvt_pk(o1[2], o1[3]);
;                         *(u32x4*)(xb + off + bj * 128) = w;
;                         q += (o0[0] * o0[0] + o0[1] * o0[1]) + (o0[2] * o0[2] + o0[3] * o0[3]) + (o1[0] * o1[0] + o1[1] * o1[1]) + (o1[2] * o1[2] + o1[3] * o1[3]);
;                     }
;                 }
;                 if (xb) { q += __shfl_xor(q, 16); q += __shfl_xor(q, 32); if (fq == 0) ssq[(size_t)row * 16 + u.pn * 4 + wc] = q; }
.LBB0_753:
	v_lshl_add_u32 v146, s60, 8, v148
	v_lshl_or_b32 v145, s8, 8, v150
	v_lshl_add_u32 v144, v146, 10, v145
	v_lshlrev_b32_e32 v144, 2, v144
	s_lshl_b32 s60, s8, 4
	s_lshl_b32 s61, s33, 2
	s_add_i32 s60, s60, s61
	v_lshl_add_u32 v147, v146, 6, s60
	v_xor_b32_e32 v250, 16, v154
	v_xor_b32_e32 v251, 32, v154
	v_lshlrev_b32_e32 v250, 2, v250
	v_lshlrev_b32_e32 v251, 2, v251
	v_and_b32_e32 v155, 8, v154
	v_mul_i32_i24_e32 v155, 0xfffff002, v155
	v_add_u32_e32 v144, v144, v155
	v_add_u32_e32 v253, 0x8000, v144
	global_load_dwordx4 v[156:159], v144, s[52:53] nt
	global_load_dwordx4 v[160:163], v253, s[52:53] nt
	global_load_dwordx4 v[164:167], v144, s[52:53] offset:512 nt
	global_load_dwordx4 v[168:171], v253, s[52:53] offset:512 nt
	v_add_u32_e32 v252, 0x10000, v144
	v_add_u32_e32 v253, 0x8000, v252
	global_load_dwordx4 v[172:175], v252, s[52:53] nt
	global_load_dwordx4 v[176:179], v253, s[52:53] nt
	global_load_dwordx4 v[180:183], v252, s[52:53] offset:512 nt
	global_load_dwordx4 v[184:187], v253, s[52:53] offset:512 nt
	v_add_u32_e32 v252, 0x20000, v144
	v_add_u32_e32 v253, 0x8000, v252
	global_load_dwordx4 v[188:191], v252, s[52:53] nt
	global_load_dwordx4 v[192:195], v253, s[52:53] nt
	global_load_dwordx4 v[196:199], v252, s[52:53] offset:512 nt
	global_load_dwordx4 v[200:203], v253, s[52:53] offset:512 nt
	v_add_u32_e32 v252, 0x30000, v144
	v_add_u32_e32 v253, 0x8000, v252
	global_load_dwordx4 v[204:207], v252, s[52:53] nt
	global_load_dwordx4 v[208:211], v253, s[52:53] nt
	global_load_dwordx4 v[212:215], v252, s[52:53] offset:512 nt
	global_load_dwordx4 v[216:219], v253, s[52:53] offset:512 nt
	v_add_u32_e32 v252, 0x80000, v144
	v_add_u32_e32 v253, 0x8000, v252
	global_load_dwordx4 v[220:223], v252, s[52:53] nt
	global_load_dwordx4 v[226:229], v253, s[52:53] nt
	global_load_dwordx4 v[230:233], v252, s[52:53] offset:512 nt
	global_load_dwordx4 v[236:239], v253, s[52:53] offset:512 nt
	v_mov_b32_dpp v240, v120 row_ror:8 row_mask:0xf bank_mask:0xf
	v_mov_b32_dpp v241, v121 row_ror:8 row_mask:0xf bank_mask:0xf
	v_mov_b32_dpp v242, v122 row_ror:8 row_mask:0xf bank_mask:0xf
	v_mov_b32_dpp v243, v123 row_ror:8 row_mask:0xf bank_mask:0xf
	v_mov_b32_dpp v120, v124 row_ror:8 row_mask:0xf bank_mask:0x3
	v_mov_b32_dpp v121, v125 row_ror:8 row_mask:0xf bank_mask:0x3
	v_mov_b32_dpp v122, v126 row_ror:8 row_mask:0xf bank_mask:0x3
	v_mov_b32_dpp v123, v127 row_ror:8 row_mask:0xf bank_mask:0x3
	v_mov_b32_dpp v124, v240 quad_perm:[0,1,2,3] row_mask:0xf bank_mask:0xc
	v_mov_b32_dpp v125, v241 quad_perm:[0,1,2,3] row_mask:0xf bank_mask:0xc
	v_mov_b32_dpp v126, v242 quad_perm:[0,1,2,3] row_mask:0xf bank_mask:0xc
	v_mov_b32_dpp v127, v243 quad_perm:[0,1,2,3] row_mask:0xf bank_mask:0xc
	v_mov_b32_dpp v240, v112 row_ror:8 row_mask:0xf bank_mask:0xf
	v_mov_b32_dpp v241, v113 row_ror:8 row_mask:0xf bank_mask:0xf
	v_mov_b32_dpp v242, v114 row_ror:8 row_mask:0xf bank_mask:0xf
	v_mov_b32_dpp v243, v115 row_ror:8 row_mask:0xf bank_mask:0xf
	v_mov_b32_dpp v112, v116 row_ror:8 row_mask:0xf bank_mask:0x3
	v_mov_b32_dpp v113, v117 row_ror:8 row_mask:0xf bank_mask:0x3
	v_mov_b32_dpp v114, v118 row_ror:8 row_mask:0xf bank_mask:0x3
	v_mov_b32_dpp v115, v119 row_ror:8 row_mask:0xf bank_mask:0x3
	v_mov_b32_dpp v116, v240 quad_perm:[0,1,2,3] row_mask:0xf bank_mask:0xc
	v_mov_b32_dpp v117, v241 quad_perm:[0,1,2,3] row_mask:0xf bank_mask:0xc
	v_mov_b32_dpp v118, v242 quad_perm:[0,1,2,3] row_mask:0xf bank_mask:0xc
	v_mov_b32_dpp v119, v243 quad_perm:[0,1,2,3] row_mask:0xf bank_mask:0xc
	s_waitcnt vmcnt(16)
	v_pk_add_f32 v[124:125], v[124:125], v[156:157]
	v_pk_add_f32 v[126:127], v[126:127], v[158:159]
	v_pk_add_f32 v[120:121], v[120:121], v[160:161]
	v_pk_add_f32 v[122:123], v[122:123], v[162:163]
	v_pk_add_f32 v[116:117], v[116:117], v[164:165]
	v_pk_add_f32 v[118:119], v[118:119], v[166:167]
	v_pk_add_f32 v[112:113], v[112:113], v[168:169]
	v_pk_add_f32 v[114:115], v[114:115], v[170:171]
	v_add_u32_e32 v253, 0x8000, v144
	global_store_dwordx4 v144, v[124:127], s[54:55]
	global_store_dwordx4 v253, v[120:123], s[54:55]
	global_store_dwordx4 v144, v[116:119], s[54:55] offset:512
	global_store_dwordx4 v253, v[112:115], s[54:55] offset:512
	v_cvt_pk_bf16_f32 v240, v124, v125
	v_cvt_pk_bf16_f32 v241, v126, v127
	v_cvt_pk_bf16_f32 v242, v120, v121
	v_cvt_pk_bf16_f32 v243, v122, v123
	v_cvt_pk_bf16_f32 v244, v116, v117
	v_cvt_pk_bf16_f32 v245, v118, v119
	v_cvt_pk_bf16_f32 v246, v112, v113
	v_cvt_pk_bf16_f32 v247, v114, v115
	v_lshrrev_b32_e32 v254, 1, v144
	v_lshrrev_b32_e32 v253, 1, v253
	global_store_dwordx2 v254, v[240:241], s[40:41]
	global_store_dwordx2 v253, v[242:243], s[40:41]
	global_store_dwordx2 v254, v[244:245], s[40:41] offset:256
	global_store_dwordx2 v253, v[246:247], s[40:41] offset:256
	v_mul_f32_e32 v248, v124, v124
	v_mul_f32_e32 v249, v120, v120
	v_fmac_f32_e32 v248, v125, v125
	v_fmac_f32_e32 v249, v121, v121
	v_fmac_f32_e32 v248, v126, v126
	v_fmac_f32_e32 v249, v122, v122
	v_fmac_f32_e32 v248, v127, v127
	v_fmac_f32_e32 v249, v123, v123
	v_fmac_f32_e32 v248, v116, v116
	v_fmac_f32_e32 v249, v112, v112
	v_fmac_f32_e32 v248, v117, v117
	v_fmac_f32_e32 v249, v113, v113
	v_fmac_f32_e32 v248, v118, v118
	v_fmac_f32_e32 v249, v114, v114
	v_fmac_f32_e32 v248, v119, v119
	v_fmac_f32_e32 v249, v115, v115
	s_nop 1
	v_mov_b32_dpp v240, v248 row_ror:8 row_mask:0xf bank_mask:0xf
	v_mov_b32_dpp v241, v249 row_ror:8 row_mask:0xf bank_mask:0xf
	s_nop 0
	v_add_f32_e32 v248, v248, v240
	v_add_f32_e32 v249, v249, v241
	s_nop 1
	v_mov_b32_dpp v248, v249 quad_perm:[0,1,2,3] row_mask:0xf bank_mask:0xc
	ds_bpermute_b32 v249, v250, v248
	s_waitcnt lgkmcnt(0)
; DI unsigned cvt_pk(float lo, float hi) { const f32x2 v = {lo, hi}; return __builtin_bit_cast(unsigned, __builtin_convertvector(v, bf16v2)); }
;     __device__ __forceinline__ void operator()(const f32x4 (&acc)[2][2][4][2], const Unit& u, int wr, int wc, int fr, int fq) const {
;         const int col0 = u.pn * 256 + wc * 32 + 8 * fq, rowbase = u.pm * 256 + wr * 64 + fr;
; #pragma unroll
;         for (int ai = 0; ai < 2; ++ai)
; #pragma unroll
;             for (int m = 0; m < 4; ++m) {
;                 const int row = rowbase + ai * 128 + m * 16; const size_t off = (size_t)row * DM + col0;
;                 float q = 0.f;
; #pragma unroll
;                 for (int bj = 0; bj < 2; ++bj) {
;                     const f32x4 r0 = *(const f32x4*)(resid + off + bj * 128), r1 = *(const f32x4*)(resid + off + bj * 128 + 4);
;                     const f32x4 o0 = r0 + acc[ai][bj][m][0], o1 = r1 + acc[ai][bj][m][1];
;                     *(f32x4*)(out + off + bj * 128) = o0; *(f32x4*)(out + off + bj * 128 + 4) = o1;
;                     if (xb) {
;                         u32x4 w; w.x = cvt_pk(o0[0], o0[1]); w.y = cvt_pk(o0[2], o0[3]); w.z = cvt_pk(o1[0], o1[1]); w.w = cvt_pk(o1[2], o1[3]);
;                         *(u32x4*)(xb + off + bj * 128) = w;
;                         q += (o0[0] * o0[0] + o0[1] * o0[1]) + (o0[2] * o0[2] + o0[3] * o0[3]) + (o1[0] * o1[0] + o1[1] * o1[1]) + (o1[2] * o1[2] + o1[3] * o1[3]);
;                     }
;                 }
;                 if (xb) { q += __shfl_xor(q, 16); q += __shfl_xor(q, 32); if (fq == 0) ssq[(size_t)row * 16 + u.pn * 4 + wc] = q; }
	v_add_f32_e32 v248, v248, v249
	ds_bpermute_b32 v249, v251, v248
	s_waitcnt lgkmcnt(0)
	v_add_f32_e32 v248, v248, v249
	s_and_saveexec_b64 s[62:63], s[0:1]
	global_store_dword v147, v248, s[6:7]
	s_or_b64 exec, exec, s[62:63]
	v_add_u32_e32 v252, 0x90000, v144
	v_add_u32_e32 v253, 0x8000, v252
	global_load_dwordx4 v[156:159], v252, s[52:53] nt
	global_load_dwordx4 v[160:163], v253, s[52:53] nt
	global_load_dwordx4 v[164:167], v252, s[52:53] offset:512 nt
	global_load_dwordx4 v[168:171], v253, s[52:53] offset:512 nt
	v_mov_b32_dpp v240, v104 row_ror:8 row_mask:0xf bank_mask:0xf
	v_mov_b32_dpp v241, v105 row_ror:8 row_mask:0xf bank_mask:0xf
	v_mov_b32_dpp v242, v106 row_ror:8 row_mask:0xf bank_mask:0xf
	v_mov_b32_dpp v243, v107 row_ror:8 row_mask:0xf bank_mask:0xf
	v_mov_b32_dpp v104, v108 row_ror:8 row_mask:0xf bank_mask:0x3
	v_mov_b32_dpp v105, v109 row_ror:8 row_mask:0xf bank_mask:0x3
	v_mov_b32_dpp v106, v110 row_ror:8 row_mask:0xf bank_mask:0x3
	v_mov_b32_dpp v107, v111 row_ror:8 row_mask:0xf bank_mask:0x3
	v_mov_b32_dpp v108, v240 quad_perm:[0,1,2,3] row_mask:0xf bank_mask:0xc
	v_mov_b32_dpp v109, v241 quad_perm:[0,1,2,3] row_mask:0xf bank_mask:0xc
	v_mov_b32_dpp v110, v242 quad_perm:[0,1,2,3] row_mask:0xf bank_mask:0xc
	v_mov_b32_dpp v111, v243 quad_perm:[0,1,2,3] row_mask:0xf bank_mask:0xc
	v_mov_b32_dpp v240, v96 row_ror:8 row_mask:0xf bank_mask:0xf
	v_mov_b32_dpp v241, v97 row_ror:8 row_mask:0xf bank_mask:0xf
	v_mov_b32_dpp v242, v98 row_ror:8 row_mask:0xf bank_mask:0xf
	v_mov_b32_dpp v243, v99 row_ror:8 row_mask:0xf bank_mask:0xf
	v_mov_b32_dpp v96, v100 row_ror:8 row_mask:0xf bank_mask:0x3
	v_mov_b32_dpp v97, v101 row_ror:8 row_mask:0xf bank_mask:0x3
	v_mov_b32_dpp v98, v102 row_ror:8 row_mask:0xf bank_mask:0x3
	v_mov_b32_dpp v99, v103 row_ror:8 row_mask:0xf bank_mask:0x3
	v_mov_b32_dpp v100, v240 quad_perm:[0,1,2,3] row_mask:0xf bank_mask:0xc
	v_mov_b32_dpp v101, v241 quad_perm:[0,1,2,3] row_mask:0xf bank_mask:0xc
	v_mov_b32_dpp v102, v242 quad_perm:[0,1,2,3] row_mask:0xf bank_mask:0xc
	v_mov_b32_dpp v103, v243 quad_perm:[0,1,2,3] row_mask:0xf bank_mask:0xc
	s_waitcnt vmcnt(25)
	v_pk_add_f32 v[108:109], v[108:109], v[172:173]
	v_pk_add_f32 v[110:111], v[110:111], v[174:175]
	v_pk_add_f32 v[104:105], v[104:105], v[176:177]
	v_pk_add_f32 v[106:107], v[106:107], v[178:179]
	v_pk_add_f32 v[100:101], v[100:101], v[180:181]
	v_pk_add_f32 v[102:103], v[102:103], v[182:183]
	v_pk_add_f32 v[96:97], v[96:97], v[184:185]
	v_pk_add_f32 v[98:99], v[98:99], v[186:187]
	v_add_u32_e32 v252, 0x10000, v144
	v_add_u32_e32 v253, 0x8000, v252
	global_store_dwordx4 v252, v[108:111], s[54:55]
	global_store_dwordx4 v253, v[104:107], s[54:55]
	global_store_dwordx4 v252, v[100:103], s[54:55] offset:512
	global_store_dwordx4 v253, v[96:99], s[54:55] offset:512
	v_cvt_pk_bf16_f32 v240, v108, v109
	v_cvt_pk_bf16_f32 v241, v110, v111
	v_cvt_pk_bf16_f32 v242, v104, v105
	v_cvt_pk_bf16_f32 v243, v106, v107
	v_cvt_pk_bf16_f32 v244, v100, v101
	v_cvt_pk_bf16_f32 v245, v102, v103
	v_cvt_pk_bf16_f32 v246, v96, v97
	v_cvt_pk_bf16_f32 v247, v98, v99
	v_lshrrev_b32_e32 v254, 1, v252
	v_lshrrev_b32_e32 v253, 1, v253
	global_store_dwordx2 v254, v[240:241], s[40:41]
	global_store_dwordx2 v253, v[242:243], s[40:41]
	global_store_dwordx2 v254, v[244:245], s[40:41] offset:256
	global_store_dwordx2 v253, v[246:247], s[40:41] offset:256
	v_mul_f32_e32 v248, v108, v108
	v_mul_f32_e32 v249, v104, v104
	v_fmac_f32_e32 v248, v109, v109
	v_fmac_f32_e32 v249, v105, v105
	v_fmac_f32_e32 v248, v110, v110
	v_fmac_f32_e32 v249, v106, v106
	v_fmac_f32_e32 v248, v111, v111
	v_fmac_f32_e32 v249, v107, v107
	v_fmac_f32_e32 v248, v100, v100
	v_fmac_f32_e32 v249, v96, v96
	v_fmac_f32_e32 v248, v101, v101
	v_fmac_f32_e32 v249, v97, v97
	v_fmac_f32_e32 v248, v102, v102
	v_fmac_f32_e32 v249, v98, v98
	v_fmac_f32_e32 v248, v103, v103
	v_fmac_f32_e32 v249, v99, v99
	s_nop 1
	v_mov_b32_dpp v240, v248 row_ror:8 row_mask:0xf bank_mask:0xf
	v_mov_b32_dpp v241, v249 row_ror:8 row_mask:0xf bank_mask:0xf
	s_nop 0
	v_add_f32_e32 v248, v248, v240
	v_add_f32_e32 v249, v249, v241
	s_nop 1
	v_mov_b32_dpp v248, v249 quad_perm:[0,1,2,3] row_mask:0xf bank_mask:0xc
	ds_bpermute_b32 v249, v250, v248
	s_waitcnt lgkmcnt(0)
	v_add_f32_e32 v248, v248, v249
	ds_bpermute_b32 v249, v251, v248
	v_add_u32_e32 v254, 0x400, v147
	s_waitcnt lgkmcnt(0)
	v_add_f32_e32 v248, v248, v249
	s_and_saveexec_b64 s[62:63], s[0:1]
	global_store_dword v254, v248, s[6:7]
	s_or_b64 exec, exec, s[62:63]
	v_add_u32_e32 v252, 0xa0000, v144
	v_add_u32_e32 v253, 0x8000, v252
	global_load_dwordx4 v[172:175], v252, s[52:53] nt
	global_load_dwordx4 v[176:179], v253, s[52:53] nt
	global_load_dwordx4 v[180:183], v252, s[52:53] offset:512 nt
	global_load_dwordx4 v[184:187], v253, s[52:53] offset:512 nt
	v_mov_b32_dpp v240, v88 row_ror:8 row_mask:0xf bank_mask:0xf
	v_mov_b32_dpp v241, v89 row_ror:8 row_mask:0xf bank_mask:0xf
	v_mov_b32_dpp v242, v90 row_ror:8 row_mask:0xf bank_mask:0xf
	v_mov_b32_dpp v243, v91 row_ror:8 row_mask:0xf bank_mask:0xf
	v_mov_b32_dpp v88, v92 row_ror:8 row_mask:0xf bank_mask:0x3
	v_mov_b32_dpp v89, v93 row_ror:8 row_mask:0xf bank_mask:0x3
	v_mov_b32_dpp v90, v94 row_ror:8 row_mask:0xf bank_mask:0x3
	v_mov_b32_dpp v91, v95 row_ror:8 row_mask:0xf bank_mask:0x3
	v_mov_b32_dpp v92, v240 quad_perm:[0,1,2,3] row_mask:0xf bank_mask:0xc
	v_mov_b32_dpp v93, v241 quad_perm:[0,1,2,3] row_mask:0xf bank_mask:0xc
	v_mov_b32_dpp v94, v242 quad_perm:[0,1,2,3] row_mask:0xf bank_mask:0xc
	v_mov_b32_dpp v95, v243 quad_perm:[0,1,2,3] row_mask:0xf bank_mask:0xc
	v_mov_b32_dpp v240, v80 row_ror:8 row_mask:0xf bank_mask:0xf
	v_mov_b32_dpp v241, v81 row_ror:8 row_mask:0xf bank_mask:0xf
	v_mov_b32_dpp v242, v82 row_ror:8 row_mask:0xf bank_mask:0xf
	v_mov_b32_dpp v243, v83 row_ror:8 row_mask:0xf bank_mask:0xf
	v_mov_b32_dpp v80, v84 row_ror:8 row_mask:0xf bank_mask:0x3
	v_mov_b32_dpp v81, v85 row_ror:8 row_mask:0xf bank_mask:0x3
	v_mov_b32_dpp v82, v86 row_ror:8 row_mask:0xf bank_mask:0x3
	v_mov_b32_dpp v83, v87 row_ror:8 row_mask:0xf bank_mask:0x3
	v_mov_b32_dpp v84, v240 quad_perm:[0,1,2,3] row_mask:0xf bank_mask:0xc
	v_mov_b32_dpp v85, v241 quad_perm:[0,1,2,3] row_mask:0xf bank_mask:0xc
	v_mov_b32_dpp v86, v242 quad_perm:[0,1,2,3] row_mask:0xf bank_mask:0xc
	v_mov_b32_dpp v87, v243 quad_perm:[0,1,2,3] row_mask:0xf bank_mask:0xc
	s_waitcnt vmcnt(34)
; DI unsigned cvt_pk(float lo, float hi) { const f32x2 v = {lo, hi}; return __builtin_bit_cast(unsigned, __builtin_convertvector(v, bf16v2)); }
;     __device__ __forceinline__ void operator()(const f32x4 (&acc)[2][2][4][2], const Unit& u, int wr, int wc, int fr, int fq) const {
;         const int col0 = u.pn * 256 + wc * 32 + 8 * fq, rowbase = u.pm * 256 + wr * 64 + fr;
; #pragma unroll
;         for (int ai = 0; ai < 2; ++ai)
; #pragma unroll
;             for (int m = 0; m < 4; ++m) {
;                 const int row = rowbase + ai * 128 + m * 16; const size_t off = (size_t)row * DM + col0;
;                 float q = 0.f;
; #pragma unroll
;                 for (int bj = 0; bj < 2; ++bj) {
;                     const f32x4 r0 = *(const f32x4*)(resid + off + bj * 128), r1 = *(const f32x4*)(resid + off + bj * 128 + 4);
;                     const f32x4 o0 = r0 + acc[ai][bj][m][0], o1 = r1 + acc[ai][bj][m][1];
;                     *(f32x4*)(out + off + bj * 128) = o0; *(f32x4*)(out + off + bj * 128 + 4) = o1;
;                     if (xb) {
;                         u32x4 w; w.x = cvt_pk(o0[0], o0[1]); w.y = cvt_pk(o0[2], o0[3]); w.z = cvt_pk(o1[0], o1[1]); w.w = cvt_pk(o1[2], o1[3]);
;                         *(u32x4*)(xb + off + bj * 128) = w;
;                         q += (o0[0] * o0[0] + o0[1] * o0[1]) + (o0[2] * o0[2] + o0[3] * o0[3]) + (o1[0] * o1[0] + o1[1] * o1[1]) + (o1[2] * o1[2] + o1[3] * o1[3]);
;                     }
;                 }
;                 if (xb) { q += __shfl_xor(q, 16); q += __shfl_xor(q, 32); if (fq == 0) ssq[(size_t)row * 16 + u.pn * 4 + wc] = q; }
	v_pk_add_f32 v[92:93], v[92:93], v[188:189]
	v_pk_add_f32 v[94:95], v[94:95], v[190:191]
	v_pk_add_f32 v[88:89], v[88:89], v[192:193]
	v_pk_add_f32 v[90:91], v[90:91], v[194:195]
	v_pk_add_f32 v[84:85], v[84:85], v[196:197]
	v_pk_add_f32 v[86:87], v[86:87], v[198:199]
	v_pk_add_f32 v[80:81], v[80:81], v[200:201]
	v_pk_add_f32 v[82:83], v[82:83], v[202:203]
	v_add_u32_e32 v252, 0x20000, v144
	v_add_u32_e32 v253, 0x8000, v252
	global_store_dwordx4 v252, v[92:95], s[54:55]
	global_store_dwordx4 v253, v[88:91], s[54:55]
	global_store_dwordx4 v252, v[84:87], s[54:55] offset:512
	global_store_dwordx4 v253, v[80:83], s[54:55] offset:512
	v_cvt_pk_bf16_f32 v240, v92, v93
	v_cvt_pk_bf16_f32 v241, v94, v95
	v_cvt_pk_bf16_f32 v242, v88, v89
	v_cvt_pk_bf16_f32 v243, v90, v91
	v_cvt_pk_bf16_f32 v244, v84, v85
	v_cvt_pk_bf16_f32 v245, v86, v87
	v_cvt_pk_bf16_f32 v246, v80, v81
	v_cvt_pk_bf16_f32 v247, v82, v83
	v_lshrrev_b32_e32 v254, 1, v252
	v_lshrrev_b32_e32 v253, 1, v253
	global_store_dwordx2 v254, v[240:241], s[40:41]
	global_store_dwordx2 v253, v[242:243], s[40:41]
	global_store_dwordx2 v254, v[244:245], s[40:41] offset:256
	global_store_dwordx2 v253, v[246:247], s[40:41] offset:256
	v_mul_f32_e32 v248, v92, v92
	v_mul_f32_e32 v249, v88, v88
	v_fmac_f32_e32 v248, v93, v93
	v_fmac_f32_e32 v249, v89, v89
	v_fmac_f32_e32 v248, v94, v94
	v_fmac_f32_e32 v249, v90, v90
	v_fmac_f32_e32 v248, v95, v95
	v_fmac_f32_e32 v249, v91, v91
	v_fmac_f32_e32 v248, v84, v84
	v_fmac_f32_e32 v249, v80, v80
	v_fmac_f32_e32 v248, v85, v85
	v_fmac_f32_e32 v249, v81, v81
	v_fmac_f32_e32 v248, v86, v86
	v_fmac_f32_e32 v249, v82, v82
	v_fmac_f32_e32 v248, v87, v87
	v_fmac_f32_e32 v249, v83, v83
	s_nop 1
	v_mov_b32_dpp v240, v248 row_ror:8 row_mask:0xf bank_mask:0xf
	v_mov_b32_dpp v241, v249 row_ror:8 row_mask:0xf bank_mask:0xf
	s_nop 0
	v_add_f32_e32 v248, v248, v240
	v_add_f32_e32 v249, v249, v241
	s_nop 1
	v_mov_b32_dpp v248, v249 quad_perm:[0,1,2,3] row_mask:0xf bank_mask:0xc
	ds_bpermute_b32 v249, v250, v248
	s_waitcnt lgkmcnt(0)
	v_add_f32_e32 v248, v248, v249
	ds_bpermute_b32 v249, v251, v248
	v_add_u32_e32 v254, 0x800, v147
	s_waitcnt lgkmcnt(0)
	v_add_f32_e32 v248, v248, v249
	s_and_saveexec_b64 s[62:63], s[0:1]
	global_store_dword v254, v248, s[6:7]
	s_or_b64 exec, exec, s[62:63]
	v_add_u32_e32 v252, 0xb0000, v144
	v_add_u32_e32 v253, 0x8000, v252
	global_load_dwordx4 v[188:191], v252, s[52:53] nt
	global_load_dwordx4 v[192:195], v253, s[52:53] nt
	global_load_dwordx4 v[196:199], v252, s[52:53] offset:512 nt
	global_load_dwordx4 v[200:203], v253, s[52:53] offset:512 nt
	v_mov_b32_dpp v240, v72 row_ror:8 row_mask:0xf bank_mask:0xf
	v_mov_b32_dpp v241, v73 row_ror:8 row_mask:0xf bank_mask:0xf
	v_mov_b32_dpp v242, v74 row_ror:8 row_mask:0xf bank_mask:0xf
	v_mov_b32_dpp v243, v75 row_ror:8 row_mask:0xf bank_mask:0xf
	v_mov_b32_dpp v72, v76 row_ror:8 row_mask:0xf bank_mask:0x3
	v_mov_b32_dpp v73, v77 row_ror:8 row_mask:0xf bank_mask:0x3
	v_mov_b32_dpp v74, v78 row_ror:8 row_mask:0xf bank_mask:0x3
	v_mov_b32_dpp v75, v79 row_ror:8 row_mask:0xf bank_mask:0x3
	v_mov_b32_dpp v76, v240 quad_perm:[0,1,2,3] row_mask:0xf bank_mask:0xc
	v_mov_b32_dpp v77, v241 quad_perm:[0,1,2,3] row_mask:0xf bank_mask:0xc
	v_mov_b32_dpp v78, v242 quad_perm:[0,1,2,3] row_mask:0xf bank_mask:0xc
	v_mov_b32_dpp v79, v243 quad_perm:[0,1,2,3] row_mask:0xf bank_mask:0xc
	v_mov_b32_dpp v240, v64 row_ror:8 row_mask:0xf bank_mask:0xf
	v_mov_b32_dpp v241, v65 row_ror:8 row_mask:0xf bank_mask:0xf
	v_mov_b32_dpp v242, v66 row_ror:8 row_mask:0xf bank_mask:0xf
	v_mov_b32_dpp v243, v67 row_ror:8 row_mask:0xf bank_mask:0xf
	v_mov_b32_dpp v64, v68 row_ror:8 row_mask:0xf bank_mask:0x3
	v_mov_b32_dpp v65, v69 row_ror:8 row_mask:0xf bank_mask:0x3
	v_mov_b32_dpp v66, v70 row_ror:8 row_mask:0xf bank_mask:0x3
	v_mov_b32_dpp v67, v71 row_ror:8 row_mask:0xf bank_mask:0x3
	v_mov_b32_dpp v68, v240 quad_perm:[0,1,2,3] row_mask:0xf bank_mask:0xc
	v_mov_b32_dpp v69, v241 quad_perm:[0,1,2,3] row_mask:0xf bank_mask:0xc
	v_mov_b32_dpp v70, v242 quad_perm:[0,1,2,3] row_mask:0xf bank_mask:0xc
	v_mov_b32_dpp v71, v243 quad_perm:[0,1,2,3] row_mask:0xf bank_mask:0xc
	s_waitcnt vmcnt(43)
	v_pk_add_f32 v[76:77], v[76:77], v[204:205]
	v_pk_add_f32 v[78:79], v[78:79], v[206:207]
	v_pk_add_f32 v[72:73], v[72:73], v[208:209]
	v_pk_add_f32 v[74:75], v[74:75], v[210:211]
	v_pk_add_f32 v[68:69], v[68:69], v[212:213]
	v_pk_add_f32 v[70:71], v[70:71], v[214:215]
	v_pk_add_f32 v[64:65], v[64:65], v[216:217]
	v_pk_add_f32 v[66:67], v[66:67], v[218:219]
	v_add_u32_e32 v252, 0x30000, v144
	v_add_u32_e32 v253, 0x8000, v252
	global_store_dwordx4 v252, v[76:79], s[54:55]
	global_store_dwordx4 v253, v[72:75], s[54:55]
	global_store_dwordx4 v252, v[68:71], s[54:55] offset:512
	global_store_dwordx4 v253, v[64:67], s[54:55] offset:512
	v_cvt_pk_bf16_f32 v240, v76, v77
	v_cvt_pk_bf16_f32 v241, v78, v79
	v_cvt_pk_bf16_f32 v242, v72, v73
	v_cvt_pk_bf16_f32 v243, v74, v75
	v_cvt_pk_bf16_f32 v244, v68, v69
	v_cvt_pk_bf16_f32 v245, v70, v71
	v_cvt_pk_bf16_f32 v246, v64, v65
	v_cvt_pk_bf16_f32 v247, v66, v67
	v_lshrrev_b32_e32 v254, 1, v252
	v_lshrrev_b32_e32 v253, 1, v253
	global_store_dwordx2 v254, v[240:241], s[40:41]
	global_store_dwordx2 v253, v[242:243], s[40:41]
	global_store_dwordx2 v254, v[244:245], s[40:41] offset:256
	global_store_dwordx2 v253, v[246:247], s[40:41] offset:256
	v_mul_f32_e32 v248, v76, v76
	v_mul_f32_e32 v249, v72, v72
	v_fmac_f32_e32 v248, v77, v77
	v_fmac_f32_e32 v249, v73, v73
	v_fmac_f32_e32 v248, v78, v78
	v_fmac_f32_e32 v249, v74, v74
	v_fmac_f32_e32 v248, v79, v79
	v_fmac_f32_e32 v249, v75, v75
	v_fmac_f32_e32 v248, v68, v68
	v_fmac_f32_e32 v249, v64, v64
	v_fmac_f32_e32 v248, v69, v69
	v_fmac_f32_e32 v249, v65, v65
	v_fmac_f32_e32 v248, v70, v70
	v_fmac_f32_e32 v249, v66, v66
	v_fmac_f32_e32 v248, v71, v71
	v_fmac_f32_e32 v249, v67, v67
	s_nop 1
	v_mov_b32_dpp v240, v248 row_ror:8 row_mask:0xf bank_mask:0xf
	v_mov_b32_dpp v241, v249 row_ror:8 row_mask:0xf bank_mask:0xf
	s_nop 0
	v_add_f32_e32 v248, v248, v240
	v_add_f32_e32 v249, v249, v241
	s_nop 1
	v_mov_b32_dpp v248, v249 quad_perm:[0,1,2,3] row_mask:0xf bank_mask:0xc
	ds_bpermute_b32 v249, v250, v248
	s_waitcnt lgkmcnt(0)
; DI unsigned cvt_pk(float lo, float hi) { const f32x2 v = {lo, hi}; return __builtin_bit_cast(unsigned, __builtin_convertvector(v, bf16v2)); }
;     __device__ __forceinline__ void operator()(const f32x4 (&acc)[2][2][4][2], const Unit& u, int wr, int wc, int fr, int fq) const {
;         const int col0 = u.pn * 256 + wc * 32 + 8 * fq, rowbase = u.pm * 256 + wr * 64 + fr;
; #pragma unroll
;         for (int ai = 0; ai < 2; ++ai)
; #pragma unroll
;             for (int m = 0; m < 4; ++m) {
;                 const int row = rowbase + ai * 128 + m * 16; const size_t off = (size_t)row * DM + col0;
;                 float q = 0.f;
; #pragma unroll
;                 for (int bj = 0; bj < 2; ++bj) {
;                     const f32x4 r0 = *(const f32x4*)(resid + off + bj * 128), r1 = *(const f32x4*)(resid + off + bj * 128 + 4);
;                     const f32x4 o0 = r0 + acc[ai][bj][m][0], o1 = r1 + acc[ai][bj][m][1];
;                     *(f32x4*)(out + off + bj * 128) = o0; *(f32x4*)(out + off + bj * 128 + 4) = o1;
;                     if (xb) {
;                         u32x4 w; w.x = cvt_pk(o0[0], o0[1]); w.y = cvt_pk(o0[2], o0[3]); w.z = cvt_pk(o1[0], o1[1]); w.w = cvt_pk(o1[2], o1[3]);
;                         *(u32x4*)(xb + off + bj * 128) = w;
;                         q += (o0[0] * o0[0] + o0[1] * o0[1]) + (o0[2] * o0[2] + o0[3] * o0[3]) + (o1[0] * o1[0] + o1[1] * o1[1]) + (o1[2] * o1[2] + o1[3] * o1[3]);
;                     }
;                 }
;                 if (xb) { q += __shfl_xor(q, 16); q += __shfl_xor(q, 32); if (fq == 0) ssq[(size_t)row * 16 + u.pn * 4 + wc] = q; }
	v_add_f32_e32 v248, v248, v249
	ds_bpermute_b32 v249, v251, v248
	v_add_u32_e32 v254, 0xc00, v147
	s_waitcnt lgkmcnt(0)
	v_add_f32_e32 v248, v248, v249
	s_and_saveexec_b64 s[62:63], s[0:1]
	global_store_dword v254, v248, s[6:7]
	s_or_b64 exec, exec, s[62:63]
	v_mov_b32_dpp v240, v56 row_ror:8 row_mask:0xf bank_mask:0xf
	v_mov_b32_dpp v241, v57 row_ror:8 row_mask:0xf bank_mask:0xf
	v_mov_b32_dpp v242, v58 row_ror:8 row_mask:0xf bank_mask:0xf
	v_mov_b32_dpp v243, v59 row_ror:8 row_mask:0xf bank_mask:0xf
	v_mov_b32_dpp v56, v60 row_ror:8 row_mask:0xf bank_mask:0x3
	v_mov_b32_dpp v57, v61 row_ror:8 row_mask:0xf bank_mask:0x3
	v_mov_b32_dpp v58, v62 row_ror:8 row_mask:0xf bank_mask:0x3
	v_mov_b32_dpp v59, v63 row_ror:8 row_mask:0xf bank_mask:0x3
	v_mov_b32_dpp v60, v240 quad_perm:[0,1,2,3] row_mask:0xf bank_mask:0xc
	v_mov_b32_dpp v61, v241 quad_perm:[0,1,2,3] row_mask:0xf bank_mask:0xc
	v_mov_b32_dpp v62, v242 quad_perm:[0,1,2,3] row_mask:0xf bank_mask:0xc
	v_mov_b32_dpp v63, v243 quad_perm:[0,1,2,3] row_mask:0xf bank_mask:0xc
	v_mov_b32_dpp v240, v48 row_ror:8 row_mask:0xf bank_mask:0xf
	v_mov_b32_dpp v241, v49 row_ror:8 row_mask:0xf bank_mask:0xf
	v_mov_b32_dpp v242, v50 row_ror:8 row_mask:0xf bank_mask:0xf
	v_mov_b32_dpp v243, v51 row_ror:8 row_mask:0xf bank_mask:0xf
	v_mov_b32_dpp v48, v52 row_ror:8 row_mask:0xf bank_mask:0x3
	v_mov_b32_dpp v49, v53 row_ror:8 row_mask:0xf bank_mask:0x3
	v_mov_b32_dpp v50, v54 row_ror:8 row_mask:0xf bank_mask:0x3
	v_mov_b32_dpp v51, v55 row_ror:8 row_mask:0xf bank_mask:0x3
	v_mov_b32_dpp v52, v240 quad_perm:[0,1,2,3] row_mask:0xf bank_mask:0xc
	v_mov_b32_dpp v53, v241 quad_perm:[0,1,2,3] row_mask:0xf bank_mask:0xc
	v_mov_b32_dpp v54, v242 quad_perm:[0,1,2,3] row_mask:0xf bank_mask:0xc
	v_mov_b32_dpp v55, v243 quad_perm:[0,1,2,3] row_mask:0xf bank_mask:0xc
	s_waitcnt vmcnt(48)
	v_pk_add_f32 v[60:61], v[60:61], v[220:221]
	v_pk_add_f32 v[62:63], v[62:63], v[222:223]
	v_pk_add_f32 v[56:57], v[56:57], v[226:227]
	v_pk_add_f32 v[58:59], v[58:59], v[228:229]
	v_pk_add_f32 v[52:53], v[52:53], v[230:231]
	v_pk_add_f32 v[54:55], v[54:55], v[232:233]
	v_pk_add_f32 v[48:49], v[48:49], v[236:237]
	v_pk_add_f32 v[50:51], v[50:51], v[238:239]
	v_add_u32_e32 v252, 0x80000, v144
	v_add_u32_e32 v253, 0x8000, v252
	global_store_dwordx4 v252, v[60:63], s[54:55]
	global_store_dwordx4 v253, v[56:59], s[54:55]
	global_store_dwordx4 v252, v[52:55], s[54:55] offset:512
	global_store_dwordx4 v253, v[48:51], s[54:55] offset:512
	v_cvt_pk_bf16_f32 v240, v60, v61
	v_cvt_pk_bf16_f32 v241, v62, v63
	v_cvt_pk_bf16_f32 v242, v56, v57
	v_cvt_pk_bf16_f32 v243, v58, v59
	v_cvt_pk_bf16_f32 v244, v52, v53
	v_cvt_pk_bf16_f32 v245, v54, v55
	v_cvt_pk_bf16_f32 v246, v48, v49
	v_cvt_pk_bf16_f32 v247, v50, v51
	v_lshrrev_b32_e32 v254, 1, v252
	v_lshrrev_b32_e32 v253, 1, v253
	global_store_dwordx2 v254, v[240:241], s[40:41]
	global_store_dwordx2 v253, v[242:243], s[40:41]
	global_store_dwordx2 v254, v[244:245], s[40:41] offset:256
	global_store_dwordx2 v253, v[246:247], s[40:41] offset:256
	v_mul_f32_e32 v248, v60, v60
	v_mul_f32_e32 v249, v56, v56
	v_fmac_f32_e32 v248, v61, v61
	v_fmac_f32_e32 v249, v57, v57
	v_fmac_f32_e32 v248, v62, v62
	v_fmac_f32_e32 v249, v58, v58
	v_fmac_f32_e32 v248, v63, v63
	v_fmac_f32_e32 v249, v59, v59
	v_fmac_f32_e32 v248, v52, v52
	v_fmac_f32_e32 v249, v48, v48
	v_fmac_f32_e32 v248, v53, v53
	v_fmac_f32_e32 v249, v49, v49
	v_fmac_f32_e32 v248, v54, v54
	v_fmac_f32_e32 v249, v50, v50
	v_fmac_f32_e32 v248, v55, v55
	v_fmac_f32_e32 v249, v51, v51
	s_nop 1
	v_mov_b32_dpp v240, v248 row_ror:8 row_mask:0xf bank_mask:0xf
	v_mov_b32_dpp v241, v249 row_ror:8 row_mask:0xf bank_mask:0xf
	s_nop 0
	v_add_f32_e32 v248, v248, v240
	v_add_f32_e32 v249, v249, v241
	s_nop 1
	v_mov_b32_dpp v248, v249 quad_perm:[0,1,2,3] row_mask:0xf bank_mask:0xc
	ds_bpermute_b32 v249, v250, v248
	s_waitcnt lgkmcnt(0)
	v_add_f32_e32 v248, v248, v249
	ds_bpermute_b32 v249, v251, v248
	v_add_u32_e32 v254, 0x2000, v147
	s_waitcnt lgkmcnt(0)
	v_add_f32_e32 v248, v248, v249
	s_and_saveexec_b64 s[62:63], s[0:1]
	global_store_dword v254, v248, s[6:7]
	s_or_b64 exec, exec, s[62:63]
	v_mov_b32_dpp v240, v40 row_ror:8 row_mask:0xf bank_mask:0xf
	v_mov_b32_dpp v241, v41 row_ror:8 row_mask:0xf bank_mask:0xf
	v_mov_b32_dpp v242, v42 row_ror:8 row_mask:0xf bank_mask:0xf
	v_mov_b32_dpp v243, v43 row_ror:8 row_mask:0xf bank_mask:0xf
	v_mov_b32_dpp v40, v44 row_ror:8 row_mask:0xf bank_mask:0x3
	v_mov_b32_dpp v41, v45 row_ror:8 row_mask:0xf bank_mask:0x3
	v_mov_b32_dpp v42, v46 row_ror:8 row_mask:0xf bank_mask:0x3
	v_mov_b32_dpp v43, v47 row_ror:8 row_mask:0xf bank_mask:0x3
	v_mov_b32_dpp v44, v240 quad_perm:[0,1,2,3] row_mask:0xf bank_mask:0xc
	v_mov_b32_dpp v45, v241 quad_perm:[0,1,2,3] row_mask:0xf bank_mask:0xc
	v_mov_b32_dpp v46, v242 quad_perm:[0,1,2,3] row_mask:0xf bank_mask:0xc
	v_mov_b32_dpp v47, v243 quad_perm:[0,1,2,3] row_mask:0xf bank_mask:0xc
	v_mov_b32_dpp v240, v32 row_ror:8 row_mask:0xf bank_mask:0xf
	v_mov_b32_dpp v241, v33 row_ror:8 row_mask:0xf bank_mask:0xf
	v_mov_b32_dpp v242, v34 row_ror:8 row_mask:0xf bank_mask:0xf
	v_mov_b32_dpp v243, v35 row_ror:8 row_mask:0xf bank_mask:0xf
	v_mov_b32_dpp v32, v36 row_ror:8 row_mask:0xf bank_mask:0x3
	v_mov_b32_dpp v33, v37 row_ror:8 row_mask:0xf bank_mask:0x3
	v_mov_b32_dpp v34, v38 row_ror:8 row_mask:0xf bank_mask:0x3
	v_mov_b32_dpp v35, v39 row_ror:8 row_mask:0xf bank_mask:0x3
	v_mov_b32_dpp v36, v240 quad_perm:[0,1,2,3] row_mask:0xf bank_mask:0xc
	v_mov_b32_dpp v37, v241 quad_perm:[0,1,2,3] row_mask:0xf bank_mask:0xc
	v_mov_b32_dpp v38, v242 quad_perm:[0,1,2,3] row_mask:0xf bank_mask:0xc
	v_mov_b32_dpp v39, v243 quad_perm:[0,1,2,3] row_mask:0xf bank_mask:0xc
	s_waitcnt vmcnt(44)
; DI unsigned cvt_pk(float lo, float hi) { const f32x2 v = {lo, hi}; return __builtin_bit_cast(unsigned, __builtin_convertvector(v, bf16v2)); }
;     __device__ __forceinline__ void operator()(const f32x4 (&acc)[2][2][4][2], const Unit& u, int wr, int wc, int fr, int fq) const {
;         const int col0 = u.pn * 256 + wc * 32 + 8 * fq, rowbase = u.pm * 256 + wr * 64 + fr;
; #pragma unroll
;         for (int ai = 0; ai < 2; ++ai)
; #pragma unroll
;             for (int m = 0; m < 4; ++m) {
;                 const int row = rowbase + ai * 128 + m * 16; const size_t off = (size_t)row * DM + col0;
;                 float q = 0.f;
; #pragma unroll
;                 for (int bj = 0; bj < 2; ++bj) {
;                     const f32x4 r0 = *(const f32x4*)(resid + off + bj * 128), r1 = *(const f32x4*)(resid + off + bj * 128 + 4);
;                     const f32x4 o0 = r0 + acc[ai][bj][m][0], o1 = r1 + acc[ai][bj][m][1];
;                     *(f32x4*)(out + off + bj * 128) = o0; *(f32x4*)(out + off + bj * 128 + 4) = o1;
;                     if (xb) {
;                         u32x4 w; w.x = cvt_pk(o0[0], o0[1]); w.y = cvt_pk(o0[2], o0[3]); w.z = cvt_pk(o1[0], o1[1]); w.w = cvt_pk(o1[2], o1[3]);
;                         *(u32x4*)(xb + off + bj * 128) = w;
;                         q += (o0[0] * o0[0] + o0[1] * o0[1]) + (o0[2] * o0[2] + o0[3] * o0[3]) + (o1[0] * o1[0] + o1[1] * o1[1]) + (o1[2] * o1[2] + o1[3] * o1[3]);
;                     }
;                 }
;                 if (xb) { q += __shfl_xor(q, 16); q += __shfl_xor(q, 32); if (fq == 0) ssq[(size_t)row * 16 + u.pn * 4 + wc] = q; }
	v_pk_add_f32 v[44:45], v[44:45], v[156:157]
	v_pk_add_f32 v[46:47], v[46:47], v[158:159]
	v_pk_add_f32 v[40:41], v[40:41], v[160:161]
	v_pk_add_f32 v[42:43], v[42:43], v[162:163]
	v_pk_add_f32 v[36:37], v[36:37], v[164:165]
	v_pk_add_f32 v[38:39], v[38:39], v[166:167]
	v_pk_add_f32 v[32:33], v[32:33], v[168:169]
	v_pk_add_f32 v[34:35], v[34:35], v[170:171]
	v_add_u32_e32 v252, 0x90000, v144
	v_add_u32_e32 v253, 0x8000, v252
	global_store_dwordx4 v252, v[44:47], s[54:55]
	global_store_dwordx4 v253, v[40:43], s[54:55]
	global_store_dwordx4 v252, v[36:39], s[54:55] offset:512
	global_store_dwordx4 v253, v[32:35], s[54:55] offset:512
	v_cvt_pk_bf16_f32 v240, v44, v45
	v_cvt_pk_bf16_f32 v241, v46, v47
	v_cvt_pk_bf16_f32 v242, v40, v41
	v_cvt_pk_bf16_f32 v243, v42, v43
	v_cvt_pk_bf16_f32 v244, v36, v37
	v_cvt_pk_bf16_f32 v245, v38, v39
	v_cvt_pk_bf16_f32 v246, v32, v33
	v_cvt_pk_bf16_f32 v247, v34, v35
	v_lshrrev_b32_e32 v254, 1, v252
	v_lshrrev_b32_e32 v253, 1, v253
	global_store_dwordx2 v254, v[240:241], s[40:41]
	global_store_dwordx2 v253, v[242:243], s[40:41]
	global_store_dwordx2 v254, v[244:245], s[40:41] offset:256
	global_store_dwordx2 v253, v[246:247], s[40:41] offset:256
	v_mul_f32_e32 v248, v44, v44
	v_mul_f32_e32 v249, v40, v40
	v_fmac_f32_e32 v248, v45, v45
	v_fmac_f32_e32 v249, v41, v41
	v_fmac_f32_e32 v248, v46, v46
	v_fmac_f32_e32 v249, v42, v42
	v_fmac_f32_e32 v248, v47, v47
	v_fmac_f32_e32 v249, v43, v43
	v_fmac_f32_e32 v248, v36, v36
	v_fmac_f32_e32 v249, v32, v32
	v_fmac_f32_e32 v248, v37, v37
	v_fmac_f32_e32 v249, v33, v33
	v_fmac_f32_e32 v248, v38, v38
	v_fmac_f32_e32 v249, v34, v34
	v_fmac_f32_e32 v248, v39, v39
	v_fmac_f32_e32 v249, v35, v35
	s_nop 1
	v_mov_b32_dpp v240, v248 row_ror:8 row_mask:0xf bank_mask:0xf
	v_mov_b32_dpp v241, v249 row_ror:8 row_mask:0xf bank_mask:0xf
	s_nop 0
	v_add_f32_e32 v248, v248, v240
	v_add_f32_e32 v249, v249, v241
	s_nop 1
	v_mov_b32_dpp v248, v249 quad_perm:[0,1,2,3] row_mask:0xf bank_mask:0xc
	ds_bpermute_b32 v249, v250, v248
	s_waitcnt lgkmcnt(0)
	v_add_f32_e32 v248, v248, v249
	ds_bpermute_b32 v249, v251, v248
	v_add_u32_e32 v254, 0x2400, v147
	s_waitcnt lgkmcnt(0)
	v_add_f32_e32 v248, v248, v249
	s_and_saveexec_b64 s[62:63], s[0:1]
	global_store_dword v254, v248, s[6:7]
	s_or_b64 exec, exec, s[62:63]
	v_mov_b32_dpp v240, v24 row_ror:8 row_mask:0xf bank_mask:0xf
	v_mov_b32_dpp v241, v25 row_ror:8 row_mask:0xf bank_mask:0xf
	v_mov_b32_dpp v242, v26 row_ror:8 row_mask:0xf bank_mask:0xf
	v_mov_b32_dpp v243, v27 row_ror:8 row_mask:0xf bank_mask:0xf
	v_mov_b32_dpp v24, v28 row_ror:8 row_mask:0xf bank_mask:0x3
	v_mov_b32_dpp v25, v29 row_ror:8 row_mask:0xf bank_mask:0x3
	v_mov_b32_dpp v26, v30 row_ror:8 row_mask:0xf bank_mask:0x3
	v_mov_b32_dpp v27, v31 row_ror:8 row_mask:0xf bank_mask:0x3
	v_mov_b32_dpp v28, v240 quad_perm:[0,1,2,3] row_mask:0xf bank_mask:0xc
	v_mov_b32_dpp v29, v241 quad_perm:[0,1,2,3] row_mask:0xf bank_mask:0xc
	v_mov_b32_dpp v30, v242 quad_perm:[0,1,2,3] row_mask:0xf bank_mask:0xc
	v_mov_b32_dpp v31, v243 quad_perm:[0,1,2,3] row_mask:0xf bank_mask:0xc
	v_mov_b32_dpp v240, v16 row_ror:8 row_mask:0xf bank_mask:0xf
	v_mov_b32_dpp v241, v17 row_ror:8 row_mask:0xf bank_mask:0xf
	v_mov_b32_dpp v242, v18 row_ror:8 row_mask:0xf bank_mask:0xf
	v_mov_b32_dpp v243, v19 row_ror:8 row_mask:0xf bank_mask:0xf
	v_mov_b32_dpp v16, v20 row_ror:8 row_mask:0xf bank_mask:0x3
	v_mov_b32_dpp v17, v21 row_ror:8 row_mask:0xf bank_mask:0x3
	v_mov_b32_dpp v18, v22 row_ror:8 row_mask:0xf bank_mask:0x3
	v_mov_b32_dpp v19, v23 row_ror:8 row_mask:0xf bank_mask:0x3
	v_mov_b32_dpp v20, v240 quad_perm:[0,1,2,3] row_mask:0xf bank_mask:0xc
	v_mov_b32_dpp v21, v241 quad_perm:[0,1,2,3] row_mask:0xf bank_mask:0xc
	v_mov_b32_dpp v22, v242 quad_perm:[0,1,2,3] row_mask:0xf bank_mask:0xc
	v_mov_b32_dpp v23, v243 quad_perm:[0,1,2,3] row_mask:0xf bank_mask:0xc
	s_waitcnt vmcnt(40)
	v_pk_add_f32 v[28:29], v[28:29], v[172:173]
	v_pk_add_f32 v[30:31], v[30:31], v[174:175]
	v_pk_add_f32 v[24:25], v[24:25], v[176:177]
	v_pk_add_f32 v[26:27], v[26:27], v[178:179]
	v_pk_add_f32 v[20:21], v[20:21], v[180:181]
	v_pk_add_f32 v[22:23], v[22:23], v[182:183]
	v_pk_add_f32 v[16:17], v[16:17], v[184:185]
	v_pk_add_f32 v[18:19], v[18:19], v[186:187]
	v_add_u32_e32 v252, 0xa0000, v144
	v_add_u32_e32 v253, 0x8000, v252
	global_store_dwordx4 v252, v[28:31], s[54:55]
	global_store_dwordx4 v253, v[24:27], s[54:55]
	global_store_dwordx4 v252, v[20:23], s[54:55] offset:512
	global_store_dwordx4 v253, v[16:19], s[54:55] offset:512
	v_cvt_pk_bf16_f32 v240, v28, v29
	v_cvt_pk_bf16_f32 v241, v30, v31
	v_cvt_pk_bf16_f32 v242, v24, v25
	v_cvt_pk_bf16_f32 v243, v26, v27
	v_cvt_pk_bf16_f32 v244, v20, v21
	v_cvt_pk_bf16_f32 v245, v22, v23
	v_cvt_pk_bf16_f32 v246, v16, v17
	v_cvt_pk_bf16_f32 v247, v18, v19
	v_lshrrev_b32_e32 v254, 1, v252
	v_lshrrev_b32_e32 v253, 1, v253
	global_store_dwordx2 v254, v[240:241], s[40:41]
	global_store_dwordx2 v253, v[242:243], s[40:41]
	global_store_dwordx2 v254, v[244:245], s[40:41] offset:256
	global_store_dwordx2 v253, v[246:247], s[40:41] offset:256
	v_mul_f32_e32 v248, v28, v28
	v_mul_f32_e32 v249, v24, v24
	v_fmac_f32_e32 v248, v29, v29
	v_fmac_f32_e32 v249, v25, v25
	v_fmac_f32_e32 v248, v30, v30
	v_fmac_f32_e32 v249, v26, v26
	v_fmac_f32_e32 v248, v31, v31
	v_fmac_f32_e32 v249, v27, v27
	v_fmac_f32_e32 v248, v20, v20
	v_fmac_f32_e32 v249, v16, v16
	v_fmac_f32_e32 v248, v21, v21
	v_fmac_f32_e32 v249, v17, v17
	v_fmac_f32_e32 v248, v22, v22
	v_fmac_f32_e32 v249, v18, v18
	v_fmac_f32_e32 v248, v23, v23
	v_fmac_f32_e32 v249, v19, v19
	s_nop 1
	v_mov_b32_dpp v240, v248 row_ror:8 row_mask:0xf bank_mask:0xf
	v_mov_b32_dpp v241, v249 row_ror:8 row_mask:0xf bank_mask:0xf
	s_nop 0
	v_add_f32_e32 v248, v248, v240
	v_add_f32_e32 v249, v249, v241
	s_nop 1
	v_mov_b32_dpp v248, v249 quad_perm:[0,1,2,3] row_mask:0xf bank_mask:0xc
	ds_bpermute_b32 v249, v250, v248
	s_waitcnt lgkmcnt(0)
; #define PG8_BAR __builtin_amdgcn_s_barrier()
; DI unsigned cvt_pk(float lo, float hi) { const f32x2 v = {lo, hi}; return __builtin_bit_cast(unsigned, __builtin_convertvector(v, bf16v2)); }
; template <class Epi, class Sched, bool ALIGN_EPI = false, bool SP2 = false>
; __device__ __forceinline__ void gemm_phase(PG8_LAS unsigned char* lds, const Gemm g, const Sched& S, const Epi& E) {
;     ...
;         if (!has_next) break;
; #pragma unroll
;         for (int a = 0; a < 2; ++a)
; #pragma unroll
;             for (int b = 0; b < 2; ++b)
; #pragma unroll
;                 for (int m = 0; m < 4; ++m)
; #pragma unroll
;                     for (int n = 0; n < 2; ++n) acc[a][b][m][n] = (f32x4){0.f, 0.f, 0.f, 0.f};
;         cur = nxt; cA = nA; cB = nB; ++ui;
;         if constexpr (ALIGN_EPI) { if (wr == 1) PG8_BAR; }
;     __device__ __forceinline__ void operator()(const f32x4 (&acc)[2][2][4][2], const Unit& u, int wr, int wc, int fr, int fq) const {
;         const int col0 = u.pn * 256 + wc * 32 + 8 * fq, rowbase = u.pm * 256 + wr * 64 + fr;
; #pragma unroll
;         for (int ai = 0; ai < 2; ++ai)
; #pragma unroll
;             for (int m = 0; m < 4; ++m) {
;                 const int row = rowbase + ai * 128 + m * 16; const size_t off = (size_t)row * DM + col0;
;                 float q = 0.f;
; #pragma unroll
;                 for (int bj = 0; bj < 2; ++bj) {
;                     const f32x4 r0 = *(const f32x4*)(resid + off + bj * 128), r1 = *(const f32x4*)(resid + off + bj * 128 + 4);
;                     const f32x4 o0 = r0 + acc[ai][bj][m][0], o1 = r1 + acc[ai][bj][m][1];
;                     *(f32x4*)(out + off + bj * 128) = o0; *(f32x4*)(out + off + bj * 128 + 4) = o1;
;                     if (xb) {
;                         u32x4 w; w.x = cvt_pk(o0[0], o0[1]); w.y = cvt_pk(o0[2], o0[3]); w.z = cvt_pk(o1[0], o1[1]); w.w = cvt_pk(o1[2], o1[3]);
;                         *(u32x4*)(xb + off + bj * 128) = w;
;                         q += (o0[0] * o0[0] + o0[1] * o0[1]) + (o0[2] * o0[2] + o0[3] * o0[3]) + (o1[0] * o1[0] + o1[1] * o1[1]) + (o1[2] * o1[2] + o1[3] * o1[3]);
;                     }
;                 }
;                 if (xb) { q += __shfl_xor(q, 16); q += __shfl_xor(q, 32); if (fq == 0) ssq[(size_t)row * 16 + u.pn * 4 + wc] = q; }
	v_add_f32_e32 v248, v248, v249
	ds_bpermute_b32 v249, v251, v248
	v_add_u32_e32 v254, 0x2800, v147
	s_waitcnt lgkmcnt(0)
	v_add_f32_e32 v248, v248, v249
	s_and_saveexec_b64 s[62:63], s[0:1]
	global_store_dword v254, v248, s[6:7]
	s_or_b64 exec, exec, s[62:63]
	v_mov_b32_dpp v240, v8 row_ror:8 row_mask:0xf bank_mask:0xf
	v_mov_b32_dpp v241, v9 row_ror:8 row_mask:0xf bank_mask:0xf
	v_mov_b32_dpp v242, v10 row_ror:8 row_mask:0xf bank_mask:0xf
	v_mov_b32_dpp v243, v11 row_ror:8 row_mask:0xf bank_mask:0xf
	v_mov_b32_dpp v8, v12 row_ror:8 row_mask:0xf bank_mask:0x3
	v_mov_b32_dpp v9, v13 row_ror:8 row_mask:0xf bank_mask:0x3
	v_mov_b32_dpp v10, v14 row_ror:8 row_mask:0xf bank_mask:0x3
	v_mov_b32_dpp v11, v15 row_ror:8 row_mask:0xf bank_mask:0x3
	v_mov_b32_dpp v12, v240 quad_perm:[0,1,2,3] row_mask:0xf bank_mask:0xc
	v_mov_b32_dpp v13, v241 quad_perm:[0,1,2,3] row_mask:0xf bank_mask:0xc
	v_mov_b32_dpp v14, v242 quad_perm:[0,1,2,3] row_mask:0xf bank_mask:0xc
	v_mov_b32_dpp v15, v243 quad_perm:[0,1,2,3] row_mask:0xf bank_mask:0xc
	v_mov_b32_dpp v240, v0 row_ror:8 row_mask:0xf bank_mask:0xf
	v_mov_b32_dpp v241, v1 row_ror:8 row_mask:0xf bank_mask:0xf
	v_mov_b32_dpp v242, v2 row_ror:8 row_mask:0xf bank_mask:0xf
	v_mov_b32_dpp v243, v3 row_ror:8 row_mask:0xf bank_mask:0xf
	v_mov_b32_dpp v0, v4 row_ror:8 row_mask:0xf bank_mask:0x3
	v_mov_b32_dpp v1, v5 row_ror:8 row_mask:0xf bank_mask:0x3
	v_mov_b32_dpp v2, v6 row_ror:8 row_mask:0xf bank_mask:0x3
	v_mov_b32_dpp v3, v7 row_ror:8 row_mask:0xf bank_mask:0x3
	v_mov_b32_dpp v4, v240 quad_perm:[0,1,2,3] row_mask:0xf bank_mask:0xc
	v_mov_b32_dpp v5, v241 quad_perm:[0,1,2,3] row_mask:0xf bank_mask:0xc
	v_mov_b32_dpp v6, v242 quad_perm:[0,1,2,3] row_mask:0xf bank_mask:0xc
	v_mov_b32_dpp v7, v243 quad_perm:[0,1,2,3] row_mask:0xf bank_mask:0xc
	s_waitcnt vmcnt(36)
	v_pk_add_f32 v[12:13], v[12:13], v[188:189]
	v_pk_add_f32 v[14:15], v[14:15], v[190:191]
	v_pk_add_f32 v[8:9], v[8:9], v[192:193]
	v_pk_add_f32 v[10:11], v[10:11], v[194:195]
	v_pk_add_f32 v[4:5], v[4:5], v[196:197]
	v_pk_add_f32 v[6:7], v[6:7], v[198:199]
	v_pk_add_f32 v[0:1], v[0:1], v[200:201]
	v_pk_add_f32 v[2:3], v[2:3], v[202:203]
	v_add_u32_e32 v252, 0xb0000, v144
	v_add_u32_e32 v253, 0x8000, v252
	global_store_dwordx4 v252, v[12:15], s[54:55]
	global_store_dwordx4 v253, v[8:11], s[54:55]
	global_store_dwordx4 v252, v[4:7], s[54:55] offset:512
	global_store_dwordx4 v253, v[0:3], s[54:55] offset:512
	v_cvt_pk_bf16_f32 v240, v12, v13
	v_cvt_pk_bf16_f32 v241, v14, v15
	v_cvt_pk_bf16_f32 v242, v8, v9
	v_cvt_pk_bf16_f32 v243, v10, v11
	v_cvt_pk_bf16_f32 v244, v4, v5
	v_cvt_pk_bf16_f32 v245, v6, v7
	v_cvt_pk_bf16_f32 v246, v0, v1
	v_cvt_pk_bf16_f32 v247, v2, v3
	v_lshrrev_b32_e32 v254, 1, v252
	v_lshrrev_b32_e32 v253, 1, v253
	global_store_dwordx2 v254, v[240:241], s[40:41]
	global_store_dwordx2 v253, v[242:243], s[40:41]
	global_store_dwordx2 v254, v[244:245], s[40:41] offset:256
	global_store_dwordx2 v253, v[246:247], s[40:41] offset:256
	v_mul_f32_e32 v248, v12, v12
	v_mul_f32_e32 v249, v8, v8
	v_fmac_f32_e32 v248, v13, v13
	v_fmac_f32_e32 v249, v9, v9
	v_fmac_f32_e32 v248, v14, v14
	v_fmac_f32_e32 v249, v10, v10
	v_fmac_f32_e32 v248, v15, v15
	v_fmac_f32_e32 v249, v11, v11
	v_fmac_f32_e32 v248, v4, v4
	v_fmac_f32_e32 v249, v0, v0
	v_fmac_f32_e32 v248, v5, v5
	v_fmac_f32_e32 v249, v1, v1
	v_fmac_f32_e32 v248, v6, v6
	v_fmac_f32_e32 v249, v2, v2
	v_fmac_f32_e32 v248, v7, v7
	v_fmac_f32_e32 v249, v3, v3
	s_nop 1
	v_mov_b32_dpp v240, v248 row_ror:8 row_mask:0xf bank_mask:0xf
	v_mov_b32_dpp v241, v249 row_ror:8 row_mask:0xf bank_mask:0xf
	s_nop 0
	v_add_f32_e32 v248, v248, v240
	v_add_f32_e32 v249, v249, v241
	s_nop 1
	v_mov_b32_dpp v248, v249 quad_perm:[0,1,2,3] row_mask:0xf bank_mask:0xc
	ds_bpermute_b32 v249, v250, v248
	s_waitcnt lgkmcnt(0)
	v_add_f32_e32 v248, v248, v249
	ds_bpermute_b32 v249, v251, v248
	v_add_u32_e32 v254, 0x2c00, v147
	s_waitcnt lgkmcnt(0)
	v_add_f32_e32 v248, v248, v249
	s_and_saveexec_b64 s[62:63], s[0:1]
	global_store_dword v254, v248, s[6:7]
	s_or_b64 exec, exec, s[62:63]
	s_andn2_b64 vcc, exec, s[4:5]
	s_mov_b64 s[4:5], -1
	s_cbranch_vccnz .LBB0_742
	s_andn2_b64 vcc, exec, s[10:11]
	s_cbranch_vccnz .LBB0_741
	s_barrier
	s_branch .LBB0_741

;     __device__ __forceinline__ void operator()(const f32x4 (&acc)[2][2][4][2], const Unit& u, int wr, int wc, int fr, int fq) const {
;         const int col0 = u.pn * 256 + wc * 32 + 8 * fq, rowbase = u.pm * 256 + wr * 64 + fr;
; #pragma unroll
;         for (int ai = 0; ai < 2; ++ai)
; #pragma unroll
;             for (int m = 0; m < 4; ++m) {
;                 const int row = rowbase + ai * 128 + m * 16; const size_t off = (size_t)row * DM + col0;
;                 float q = 0.f;
; #pragma unroll
;                 for (int bj = 0; bj < 2; ++bj) {
;                     const f32x4 r0 = *(const f32x4*)(resid + off + bj * 128), r1 = *(const f32x4*)(resid + off + bj * 128 + 4);
;                     const f32x4 o0 = r0 + acc[ai][bj][m][0], o1 = r1 + acc[ai][bj][m][1];
;                     *(f32x4*)(out + off + bj * 128) = o0; *(f32x4*)(out + off + bj * 128 + 4) = o1;
.LBB0_996:
	v_lshl_add_u32 v162, s34, 8, v146
	v_lshl_or_b32 v160, s50, 8, v148
	v_lshl_add_u32 v144, v162, 10, v160
	v_lshlrev_b32_e32 v144, 2, v144
	v_mbcnt_lo_u32_b32 v145, -1, 0
	v_mbcnt_hi_u32_b32 v145, -1, v145
	v_and_b32_e32 v145, 8, v145
	v_mul_i32_i24_e32 v145, 0xfffff002, v145
	v_add_u32_e32 v232, v144, v145
	s_andn2_b64 vcc, exec, s[0:1]
	s_mov_b64 s[0:1], -1
	v_add_u32_e32 v233, 0x10000, v232
	v_add_u32_e32 v234, 0x20000, v232
	v_add_u32_e32 v235, 0x30000, v232
	v_add_u32_e32 v236, 0x80000, v232
	v_add_u32_e32 v237, 0x90000, v232
	v_add_u32_e32 v238, 0xa0000, v232
	v_add_u32_e32 v239, 0xb0000, v232
	v_add_u32_e32 v240, 0x8000, v232
	v_add_u32_e32 v241, 0x8000, v233
	v_add_u32_e32 v242, 0x8000, v234
	v_add_u32_e32 v243, 0x8000, v235
	v_add_u32_e32 v244, 0x8000, v236
	v_add_u32_e32 v245, 0x8000, v237
	v_add_u32_e32 v246, 0x8000, v238
	v_add_u32_e32 v247, 0x8000, v239
	global_load_dwordx4 v[152:155], v232, s[54:55] nt
	global_load_dwordx4 v[156:159], v240, s[54:55] nt
	global_load_dwordx4 v[160:163], v232, s[54:55] offset:512 nt
	global_load_dwordx4 v[164:167], v240, s[54:55] offset:512 nt
	global_load_dwordx4 v[168:171], v233, s[54:55] nt
	global_load_dwordx4 v[172:175], v241, s[54:55] nt
	global_load_dwordx4 v[176:179], v233, s[54:55] offset:512 nt
	global_load_dwordx4 v[180:183], v241, s[54:55] offset:512 nt
	global_load_dwordx4 v[184:187], v234, s[54:55] nt
	global_load_dwordx4 v[188:191], v242, s[54:55] nt
	global_load_dwordx4 v[192:195], v234, s[54:55] offset:512 nt
	global_load_dwordx4 v[196:199], v242, s[54:55] offset:512 nt
	global_load_dwordx4 v[200:203], v235, s[54:55] nt
	global_load_dwordx4 v[204:207], v243, s[54:55] nt
	global_load_dwordx4 v[208:211], v235, s[54:55] offset:512 nt
	global_load_dwordx4 v[212:215], v243, s[54:55] offset:512 nt
	global_load_dwordx4 v[216:219], v236, s[54:55] nt
	global_load_dwordx4 v[220:223], v244, s[54:55] nt
	global_load_dwordx4 v[224:227], v236, s[54:55] offset:512 nt
	global_load_dwordx4 v[228:231], v244, s[54:55] offset:512 nt
	v_mov_b32_dpp v248, v120 row_ror:8 row_mask:0xf bank_mask:0xf
	v_mov_b32_dpp v249, v121 row_ror:8 row_mask:0xf bank_mask:0xf
	v_mov_b32_dpp v250, v122 row_ror:8 row_mask:0xf bank_mask:0xf
	v_mov_b32_dpp v251, v123 row_ror:8 row_mask:0xf bank_mask:0xf
	v_mov_b32_dpp v120, v124 row_ror:8 row_mask:0xf bank_mask:0x3
	v_mov_b32_dpp v121, v125 row_ror:8 row_mask:0xf bank_mask:0x3
	v_mov_b32_dpp v122, v126 row_ror:8 row_mask:0xf bank_mask:0x3
	v_mov_b32_dpp v123, v127 row_ror:8 row_mask:0xf bank_mask:0x3
	v_mov_b32_dpp v124, v248 quad_perm:[0,1,2,3] row_mask:0xf bank_mask:0xc
	v_mov_b32_dpp v125, v249 quad_perm:[0,1,2,3] row_mask:0xf bank_mask:0xc
	v_mov_b32_dpp v126, v250 quad_perm:[0,1,2,3] row_mask:0xf bank_mask:0xc
	v_mov_b32_dpp v127, v251 quad_perm:[0,1,2,3] row_mask:0xf bank_mask:0xc
	s_waitcnt vmcnt(18)
	v_pk_add_f32 v[124:125], v[124:125], v[152:153]
	v_pk_add_f32 v[126:127], v[126:127], v[154:155]
	v_pk_add_f32 v[120:121], v[120:121], v[156:157]
	v_pk_add_f32 v[122:123], v[122:123], v[158:159]
	global_store_dwordx4 v232, v[124:127], s[48:49] nt
	global_store_dwordx4 v240, v[120:123], s[48:49] nt
	v_mov_b32_dpp v248, v104 row_ror:8 row_mask:0xf bank_mask:0xf
	v_mov_b32_dpp v249, v105 row_ror:8 row_mask:0xf bank_mask:0xf
	v_mov_b32_dpp v250, v106 row_ror:8 row_mask:0xf bank_mask:0xf
	v_mov_b32_dpp v251, v107 row_ror:8 row_mask:0xf bank_mask:0xf
	v_mov_b32_dpp v104, v112 row_ror:8 row_mask:0xf bank_mask:0x3
	v_mov_b32_dpp v105, v113 row_ror:8 row_mask:0xf bank_mask:0x3
	v_mov_b32_dpp v106, v114 row_ror:8 row_mask:0xf bank_mask:0x3
	v_mov_b32_dpp v107, v115 row_ror:8 row_mask:0xf bank_mask:0x3
	v_mov_b32_dpp v112, v248 quad_perm:[0,1,2,3] row_mask:0xf bank_mask:0xc
	v_mov_b32_dpp v113, v249 quad_perm:[0,1,2,3] row_mask:0xf bank_mask:0xc
	v_mov_b32_dpp v114, v250 quad_perm:[0,1,2,3] row_mask:0xf bank_mask:0xc
	v_mov_b32_dpp v115, v251 quad_perm:[0,1,2,3] row_mask:0xf bank_mask:0xc
	s_waitcnt vmcnt(18)
	v_pk_add_f32 v[112:113], v[112:113], v[160:161]
	v_pk_add_f32 v[114:115], v[114:115], v[162:163]
	v_pk_add_f32 v[104:105], v[104:105], v[164:165]
	v_pk_add_f32 v[106:107], v[106:107], v[166:167]
	global_store_dwordx4 v232, v[112:115], s[48:49] offset:512 nt
	global_store_dwordx4 v240, v[104:107], s[48:49] offset:512 nt
	v_mov_b32_dpp v248, v108 row_ror:8 row_mask:0xf bank_mask:0xf
	v_mov_b32_dpp v249, v109 row_ror:8 row_mask:0xf bank_mask:0xf
	v_mov_b32_dpp v250, v110 row_ror:8 row_mask:0xf bank_mask:0xf
	v_mov_b32_dpp v251, v111 row_ror:8 row_mask:0xf bank_mask:0xf
	v_mov_b32_dpp v108, v116 row_ror:8 row_mask:0xf bank_mask:0x3
	v_mov_b32_dpp v109, v117 row_ror:8 row_mask:0xf bank_mask:0x3
	v_mov_b32_dpp v110, v118 row_ror:8 row_mask:0xf bank_mask:0x3
	v_mov_b32_dpp v111, v119 row_ror:8 row_mask:0xf bank_mask:0x3
	v_mov_b32_dpp v116, v248 quad_perm:[0,1,2,3] row_mask:0xf bank_mask:0xc
	v_mov_b32_dpp v117, v249 quad_perm:[0,1,2,3] row_mask:0xf bank_mask:0xc
	v_mov_b32_dpp v118, v250 quad_perm:[0,1,2,3] row_mask:0xf bank_mask:0xc
	v_mov_b32_dpp v119, v251 quad_perm:[0,1,2,3] row_mask:0xf bank_mask:0xc
	s_waitcnt vmcnt(18)
;     __device__ __forceinline__ void operator()(const f32x4 (&acc)[2][2][4][2], const Unit& u, int wr, int wc, int fr, int fq) const {
;         const int col0 = u.pn * 256 + wc * 32 + 8 * fq, rowbase = u.pm * 256 + wr * 64 + fr;
; #pragma unroll
;         for (int ai = 0; ai < 2; ++ai)
; #pragma unroll
;             for (int m = 0; m < 4; ++m) {
;                 const int row = rowbase + ai * 128 + m * 16; const size_t off = (size_t)row * DM + col0;
;                 float q = 0.f;
; #pragma unroll
;                 for (int bj = 0; bj < 2; ++bj) {
;                     const f32x4 r0 = *(const f32x4*)(resid + off + bj * 128), r1 = *(const f32x4*)(resid + off + bj * 128 + 4);
;                     const f32x4 o0 = r0 + acc[ai][bj][m][0], o1 = r1 + acc[ai][bj][m][1];
;                     *(f32x4*)(out + off + bj * 128) = o0; *(f32x4*)(out + off + bj * 128 + 4) = o1;
	v_pk_add_f32 v[116:117], v[116:117], v[168:169]
	v_pk_add_f32 v[118:119], v[118:119], v[170:171]
	v_pk_add_f32 v[108:109], v[108:109], v[172:173]
	v_pk_add_f32 v[110:111], v[110:111], v[174:175]
	global_store_dwordx4 v233, v[116:119], s[48:49] nt
	global_store_dwordx4 v241, v[108:111], s[48:49] nt
	v_mov_b32_dpp v248, v88 row_ror:8 row_mask:0xf bank_mask:0xf
	v_mov_b32_dpp v249, v89 row_ror:8 row_mask:0xf bank_mask:0xf
	v_mov_b32_dpp v250, v90 row_ror:8 row_mask:0xf bank_mask:0xf
	v_mov_b32_dpp v251, v91 row_ror:8 row_mask:0xf bank_mask:0xf
	v_mov_b32_dpp v88, v96 row_ror:8 row_mask:0xf bank_mask:0x3
	v_mov_b32_dpp v89, v97 row_ror:8 row_mask:0xf bank_mask:0x3
	v_mov_b32_dpp v90, v98 row_ror:8 row_mask:0xf bank_mask:0x3
	v_mov_b32_dpp v91, v99 row_ror:8 row_mask:0xf bank_mask:0x3
	v_mov_b32_dpp v96, v248 quad_perm:[0,1,2,3] row_mask:0xf bank_mask:0xc
	v_mov_b32_dpp v97, v249 quad_perm:[0,1,2,3] row_mask:0xf bank_mask:0xc
	v_mov_b32_dpp v98, v250 quad_perm:[0,1,2,3] row_mask:0xf bank_mask:0xc
	v_mov_b32_dpp v99, v251 quad_perm:[0,1,2,3] row_mask:0xf bank_mask:0xc
	s_waitcnt vmcnt(18)
	v_pk_add_f32 v[96:97], v[96:97], v[176:177]
	v_pk_add_f32 v[98:99], v[98:99], v[178:179]
	v_pk_add_f32 v[88:89], v[88:89], v[180:181]
	v_pk_add_f32 v[90:91], v[90:91], v[182:183]
	global_store_dwordx4 v233, v[96:99], s[48:49] offset:512 nt
	global_store_dwordx4 v241, v[88:91], s[48:49] offset:512 nt
	v_mov_b32_dpp v248, v92 row_ror:8 row_mask:0xf bank_mask:0xf
	v_mov_b32_dpp v249, v93 row_ror:8 row_mask:0xf bank_mask:0xf
	v_mov_b32_dpp v250, v94 row_ror:8 row_mask:0xf bank_mask:0xf
	v_mov_b32_dpp v251, v95 row_ror:8 row_mask:0xf bank_mask:0xf
	v_mov_b32_dpp v92, v100 row_ror:8 row_mask:0xf bank_mask:0x3
	v_mov_b32_dpp v93, v101 row_ror:8 row_mask:0xf bank_mask:0x3
	v_mov_b32_dpp v94, v102 row_ror:8 row_mask:0xf bank_mask:0x3
	v_mov_b32_dpp v95, v103 row_ror:8 row_mask:0xf bank_mask:0x3
	v_mov_b32_dpp v100, v248 quad_perm:[0,1,2,3] row_mask:0xf bank_mask:0xc
	v_mov_b32_dpp v101, v249 quad_perm:[0,1,2,3] row_mask:0xf bank_mask:0xc
	v_mov_b32_dpp v102, v250 quad_perm:[0,1,2,3] row_mask:0xf bank_mask:0xc
	v_mov_b32_dpp v103, v251 quad_perm:[0,1,2,3] row_mask:0xf bank_mask:0xc
	s_waitcnt vmcnt(18)
	v_pk_add_f32 v[100:101], v[100:101], v[184:185]
	v_pk_add_f32 v[102:103], v[102:103], v[186:187]
	v_pk_add_f32 v[92:93], v[92:93], v[188:189]
	v_pk_add_f32 v[94:95], v[94:95], v[190:191]
	global_store_dwordx4 v234, v[100:103], s[48:49] nt
	global_store_dwordx4 v242, v[92:95], s[48:49] nt
	v_mov_b32_dpp v248, v72 row_ror:8 row_mask:0xf bank_mask:0xf
	v_mov_b32_dpp v249, v73 row_ror:8 row_mask:0xf bank_mask:0xf
	v_mov_b32_dpp v250, v74 row_ror:8 row_mask:0xf bank_mask:0xf
	v_mov_b32_dpp v251, v75 row_ror:8 row_mask:0xf bank_mask:0xf
	v_mov_b32_dpp v72, v80 row_ror:8 row_mask:0xf bank_mask:0x3
	v_mov_b32_dpp v73, v81 row_ror:8 row_mask:0xf bank_mask:0x3
	v_mov_b32_dpp v74, v82 row_ror:8 row_mask:0xf bank_mask:0x3
	v_mov_b32_dpp v75, v83 row_ror:8 row_mask:0xf bank_mask:0x3
	v_mov_b32_dpp v80, v248 quad_perm:[0,1,2,3] row_mask:0xf bank_mask:0xc
	v_mov_b32_dpp v81, v249 quad_perm:[0,1,2,3] row_mask:0xf bank_mask:0xc
	v_mov_b32_dpp v82, v250 quad_perm:[0,1,2,3] row_mask:0xf bank_mask:0xc
	v_mov_b32_dpp v83, v251 quad_perm:[0,1,2,3] row_mask:0xf bank_mask:0xc
	s_waitcnt vmcnt(18)
	v_pk_add_f32 v[80:81], v[80:81], v[192:193]
	v_pk_add_f32 v[82:83], v[82:83], v[194:195]
	v_pk_add_f32 v[72:73], v[72:73], v[196:197]
	v_pk_add_f32 v[74:75], v[74:75], v[198:199]
	global_store_dwordx4 v234, v[80:83], s[48:49] offset:512 nt
	global_store_dwordx4 v242, v[72:75], s[48:49] offset:512 nt
	global_load_dwordx4 v[152:155], v237, s[54:55] nt
	global_load_dwordx4 v[156:159], v245, s[54:55] nt
	global_load_dwordx4 v[160:163], v237, s[54:55] offset:512 nt
	global_load_dwordx4 v[164:167], v245, s[54:55] offset:512 nt
	global_load_dwordx4 v[168:171], v238, s[54:55] nt
	global_load_dwordx4 v[172:175], v246, s[54:55] nt
	global_load_dwordx4 v[176:179], v238, s[54:55] offset:512 nt
	global_load_dwordx4 v[180:183], v246, s[54:55] offset:512 nt
	global_load_dwordx4 v[184:187], v239, s[54:55] nt
	global_load_dwordx4 v[188:191], v247, s[54:55] nt
	global_load_dwordx4 v[192:195], v239, s[54:55] offset:512 nt
	global_load_dwordx4 v[196:199], v247, s[54:55] offset:512 nt
	v_mov_b32_dpp v248, v76 row_ror:8 row_mask:0xf bank_mask:0xf
	v_mov_b32_dpp v249, v77 row_ror:8 row_mask:0xf bank_mask:0xf
	v_mov_b32_dpp v250, v78 row_ror:8 row_mask:0xf bank_mask:0xf
	v_mov_b32_dpp v251, v79 row_ror:8 row_mask:0xf bank_mask:0xf
	v_mov_b32_dpp v76, v84 row_ror:8 row_mask:0xf bank_mask:0x3
	v_mov_b32_dpp v77, v85 row_ror:8 row_mask:0xf bank_mask:0x3
	v_mov_b32_dpp v78, v86 row_ror:8 row_mask:0xf bank_mask:0x3
	v_mov_b32_dpp v79, v87 row_ror:8 row_mask:0xf bank_mask:0x3
	v_mov_b32_dpp v84, v248 quad_perm:[0,1,2,3] row_mask:0xf bank_mask:0xc
	v_mov_b32_dpp v85, v249 quad_perm:[0,1,2,3] row_mask:0xf bank_mask:0xc
	v_mov_b32_dpp v86, v250 quad_perm:[0,1,2,3] row_mask:0xf bank_mask:0xc
	v_mov_b32_dpp v87, v251 quad_perm:[0,1,2,3] row_mask:0xf bank_mask:0xc
	s_waitcnt vmcnt(30)
	v_pk_add_f32 v[84:85], v[84:85], v[200:201]
	v_pk_add_f32 v[86:87], v[86:87], v[202:203]
	v_pk_add_f32 v[76:77], v[76:77], v[204:205]
	v_pk_add_f32 v[78:79], v[78:79], v[206:207]
	global_store_dwordx4 v235, v[84:87], s[48:49] nt
	global_store_dwordx4 v243, v[76:79], s[48:49] nt
	v_mov_b32_dpp v248, v64 row_ror:8 row_mask:0xf bank_mask:0xf
	v_mov_b32_dpp v249, v65 row_ror:8 row_mask:0xf bank_mask:0xf
	v_mov_b32_dpp v250, v66 row_ror:8 row_mask:0xf bank_mask:0xf
	v_mov_b32_dpp v251, v67 row_ror:8 row_mask:0xf bank_mask:0xf
	v_mov_b32_dpp v64, v68 row_ror:8 row_mask:0xf bank_mask:0x3
	v_mov_b32_dpp v65, v69 row_ror:8 row_mask:0xf bank_mask:0x3
	v_mov_b32_dpp v66, v70 row_ror:8 row_mask:0xf bank_mask:0x3
	v_mov_b32_dpp v67, v71 row_ror:8 row_mask:0xf bank_mask:0x3
	v_mov_b32_dpp v68, v248 quad_perm:[0,1,2,3] row_mask:0xf bank_mask:0xc
	v_mov_b32_dpp v69, v249 quad_perm:[0,1,2,3] row_mask:0xf bank_mask:0xc
	v_mov_b32_dpp v70, v250 quad_perm:[0,1,2,3] row_mask:0xf bank_mask:0xc
	v_mov_b32_dpp v71, v251 quad_perm:[0,1,2,3] row_mask:0xf bank_mask:0xc
	s_waitcnt vmcnt(30)
;     __device__ __forceinline__ void operator()(const f32x4 (&acc)[2][2][4][2], const Unit& u, int wr, int wc, int fr, int fq) const {
;         const int col0 = u.pn * 256 + wc * 32 + 8 * fq, rowbase = u.pm * 256 + wr * 64 + fr;
; #pragma unroll
;         for (int ai = 0; ai < 2; ++ai)
; #pragma unroll
;             for (int m = 0; m < 4; ++m) {
;                 const int row = rowbase + ai * 128 + m * 16; const size_t off = (size_t)row * DM + col0;
;                 float q = 0.f;
; #pragma unroll
;                 for (int bj = 0; bj < 2; ++bj) {
;                     const f32x4 r0 = *(const f32x4*)(resid + off + bj * 128), r1 = *(const f32x4*)(resid + off + bj * 128 + 4);
;                     const f32x4 o0 = r0 + acc[ai][bj][m][0], o1 = r1 + acc[ai][bj][m][1];
;                     *(f32x4*)(out + off + bj * 128) = o0; *(f32x4*)(out + off + bj * 128 + 4) = o1;
	v_pk_add_f32 v[68:69], v[68:69], v[208:209]
	v_pk_add_f32 v[70:71], v[70:71], v[210:211]
	v_pk_add_f32 v[64:65], v[64:65], v[212:213]
	v_pk_add_f32 v[66:67], v[66:67], v[214:215]
	global_store_dwordx4 v235, v[68:71], s[48:49] offset:512 nt
	global_store_dwordx4 v243, v[64:67], s[48:49] offset:512 nt
	v_mov_b32_dpp v248, v56 row_ror:8 row_mask:0xf bank_mask:0xf
	v_mov_b32_dpp v249, v57 row_ror:8 row_mask:0xf bank_mask:0xf
	v_mov_b32_dpp v250, v58 row_ror:8 row_mask:0xf bank_mask:0xf
	v_mov_b32_dpp v251, v59 row_ror:8 row_mask:0xf bank_mask:0xf
	v_mov_b32_dpp v56, v60 row_ror:8 row_mask:0xf bank_mask:0x3
	v_mov_b32_dpp v57, v61 row_ror:8 row_mask:0xf bank_mask:0x3
	v_mov_b32_dpp v58, v62 row_ror:8 row_mask:0xf bank_mask:0x3
	v_mov_b32_dpp v59, v63 row_ror:8 row_mask:0xf bank_mask:0x3
	v_mov_b32_dpp v60, v248 quad_perm:[0,1,2,3] row_mask:0xf bank_mask:0xc
	v_mov_b32_dpp v61, v249 quad_perm:[0,1,2,3] row_mask:0xf bank_mask:0xc
	v_mov_b32_dpp v62, v250 quad_perm:[0,1,2,3] row_mask:0xf bank_mask:0xc
	v_mov_b32_dpp v63, v251 quad_perm:[0,1,2,3] row_mask:0xf bank_mask:0xc
	s_waitcnt vmcnt(30)
	v_pk_add_f32 v[60:61], v[60:61], v[216:217]
	v_pk_add_f32 v[62:63], v[62:63], v[218:219]
	v_pk_add_f32 v[56:57], v[56:57], v[220:221]
	v_pk_add_f32 v[58:59], v[58:59], v[222:223]
	global_store_dwordx4 v236, v[60:63], s[48:49] nt
	global_store_dwordx4 v244, v[56:59], s[48:49] nt
	v_mov_b32_dpp v248, v40 row_ror:8 row_mask:0xf bank_mask:0xf
	v_mov_b32_dpp v249, v41 row_ror:8 row_mask:0xf bank_mask:0xf
	v_mov_b32_dpp v250, v42 row_ror:8 row_mask:0xf bank_mask:0xf
	v_mov_b32_dpp v251, v43 row_ror:8 row_mask:0xf bank_mask:0xf
	v_mov_b32_dpp v40, v48 row_ror:8 row_mask:0xf bank_mask:0x3
	v_mov_b32_dpp v41, v49 row_ror:8 row_mask:0xf bank_mask:0x3
	v_mov_b32_dpp v42, v50 row_ror:8 row_mask:0xf bank_mask:0x3
	v_mov_b32_dpp v43, v51 row_ror:8 row_mask:0xf bank_mask:0x3
	v_mov_b32_dpp v48, v248 quad_perm:[0,1,2,3] row_mask:0xf bank_mask:0xc
	v_mov_b32_dpp v49, v249 quad_perm:[0,1,2,3] row_mask:0xf bank_mask:0xc
	v_mov_b32_dpp v50, v250 quad_perm:[0,1,2,3] row_mask:0xf bank_mask:0xc
	v_mov_b32_dpp v51, v251 quad_perm:[0,1,2,3] row_mask:0xf bank_mask:0xc
	s_waitcnt vmcnt(30)
	v_pk_add_f32 v[48:49], v[48:49], v[224:225]
	v_pk_add_f32 v[50:51], v[50:51], v[226:227]
	v_pk_add_f32 v[40:41], v[40:41], v[228:229]
	v_pk_add_f32 v[42:43], v[42:43], v[230:231]
	global_store_dwordx4 v236, v[48:51], s[48:49] offset:512 nt
	global_store_dwordx4 v244, v[40:43], s[48:49] offset:512 nt
	v_mov_b32_dpp v248, v44 row_ror:8 row_mask:0xf bank_mask:0xf
	v_mov_b32_dpp v249, v45 row_ror:8 row_mask:0xf bank_mask:0xf
	v_mov_b32_dpp v250, v46 row_ror:8 row_mask:0xf bank_mask:0xf
	v_mov_b32_dpp v251, v47 row_ror:8 row_mask:0xf bank_mask:0xf
	v_mov_b32_dpp v44, v52 row_ror:8 row_mask:0xf bank_mask:0x3
	v_mov_b32_dpp v45, v53 row_ror:8 row_mask:0xf bank_mask:0x3
	v_mov_b32_dpp v46, v54 row_ror:8 row_mask:0xf bank_mask:0x3
	v_mov_b32_dpp v47, v55 row_ror:8 row_mask:0xf bank_mask:0x3
	v_mov_b32_dpp v52, v248 quad_perm:[0,1,2,3] row_mask:0xf bank_mask:0xc
	v_mov_b32_dpp v53, v249 quad_perm:[0,1,2,3] row_mask:0xf bank_mask:0xc
	v_mov_b32_dpp v54, v250 quad_perm:[0,1,2,3] row_mask:0xf bank_mask:0xc
	v_mov_b32_dpp v55, v251 quad_perm:[0,1,2,3] row_mask:0xf bank_mask:0xc
	s_waitcnt vmcnt(18)
	v_pk_add_f32 v[52:53], v[52:53], v[152:153]
	v_pk_add_f32 v[54:55], v[54:55], v[154:155]
	v_pk_add_f32 v[44:45], v[44:45], v[156:157]
	v_pk_add_f32 v[46:47], v[46:47], v[158:159]
	global_store_dwordx4 v237, v[52:55], s[48:49] nt
	global_store_dwordx4 v245, v[44:47], s[48:49] nt
	v_mov_b32_dpp v248, v24 row_ror:8 row_mask:0xf bank_mask:0xf
	v_mov_b32_dpp v249, v25 row_ror:8 row_mask:0xf bank_mask:0xf
	v_mov_b32_dpp v250, v26 row_ror:8 row_mask:0xf bank_mask:0xf
	v_mov_b32_dpp v251, v27 row_ror:8 row_mask:0xf bank_mask:0xf
	v_mov_b32_dpp v24, v32 row_ror:8 row_mask:0xf bank_mask:0x3
	v_mov_b32_dpp v25, v33 row_ror:8 row_mask:0xf bank_mask:0x3
	v_mov_b32_dpp v26, v34 row_ror:8 row_mask:0xf bank_mask:0x3
	v_mov_b32_dpp v27, v35 row_ror:8 row_mask:0xf bank_mask:0x3
	v_mov_b32_dpp v32, v248 quad_perm:[0,1,2,3] row_mask:0xf bank_mask:0xc
	v_mov_b32_dpp v33, v249 quad_perm:[0,1,2,3] row_mask:0xf bank_mask:0xc
	v_mov_b32_dpp v34, v250 quad_perm:[0,1,2,3] row_mask:0xf bank_mask:0xc
	v_mov_b32_dpp v35, v251 quad_perm:[0,1,2,3] row_mask:0xf bank_mask:0xc
	s_waitcnt vmcnt(18)
; #define PG8_BAR __builtin_amdgcn_s_barrier()
; template <class Epi, class Sched, bool ALIGN_EPI = false, bool SP2 = false>
; __device__ __forceinline__ void gemm_phase(PG8_LAS unsigned char* lds, const Gemm g, const Sched& S, const Epi& E) {
;     ...
;         if (!has_next) break;
; #pragma unroll
;         for (int a = 0; a < 2; ++a)
; #pragma unroll
;             for (int b = 0; b < 2; ++b)
; #pragma unroll
;                 for (int m = 0; m < 4; ++m)
; #pragma unroll
;                     for (int n = 0; n < 2; ++n) acc[a][b][m][n] = (f32x4){0.f, 0.f, 0.f, 0.f};
;         cur = nxt; cA = nA; cB = nB; ++ui;
;         if constexpr (ALIGN_EPI) { if (wr == 1) PG8_BAR; }
;     __device__ __forceinline__ void operator()(const f32x4 (&acc)[2][2][4][2], const Unit& u, int wr, int wc, int fr, int fq) const {
;         const int col0 = u.pn * 256 + wc * 32 + 8 * fq, rowbase = u.pm * 256 + wr * 64 + fr;
; #pragma unroll
;         for (int ai = 0; ai < 2; ++ai)
; #pragma unroll
;             for (int m = 0; m < 4; ++m) {
;                 const int row = rowbase + ai * 128 + m * 16; const size_t off = (size_t)row * DM + col0;
;                 float q = 0.f;
; #pragma unroll
;                 for (int bj = 0; bj < 2; ++bj) {
;                     const f32x4 r0 = *(const f32x4*)(resid + off + bj * 128), r1 = *(const f32x4*)(resid + off + bj * 128 + 4);
;                     const f32x4 o0 = r0 + acc[ai][bj][m][0], o1 = r1 + acc[ai][bj][m][1];
;                     *(f32x4*)(out + off + bj * 128) = o0; *(f32x4*)(out + off + bj * 128 + 4) = o1;
	v_pk_add_f32 v[32:33], v[32:33], v[160:161]
	v_pk_add_f32 v[34:35], v[34:35], v[162:163]
	v_pk_add_f32 v[24:25], v[24:25], v[164:165]
	v_pk_add_f32 v[26:27], v[26:27], v[166:167]
	global_store_dwordx4 v237, v[32:35], s[48:49] offset:512 nt
	global_store_dwordx4 v245, v[24:27], s[48:49] offset:512 nt
	v_mov_b32_dpp v248, v28 row_ror:8 row_mask:0xf bank_mask:0xf
	v_mov_b32_dpp v249, v29 row_ror:8 row_mask:0xf bank_mask:0xf
	v_mov_b32_dpp v250, v30 row_ror:8 row_mask:0xf bank_mask:0xf
	v_mov_b32_dpp v251, v31 row_ror:8 row_mask:0xf bank_mask:0xf
	v_mov_b32_dpp v28, v36 row_ror:8 row_mask:0xf bank_mask:0x3
	v_mov_b32_dpp v29, v37 row_ror:8 row_mask:0xf bank_mask:0x3
	v_mov_b32_dpp v30, v38 row_ror:8 row_mask:0xf bank_mask:0x3
	v_mov_b32_dpp v31, v39 row_ror:8 row_mask:0xf bank_mask:0x3
	v_mov_b32_dpp v36, v248 quad_perm:[0,1,2,3] row_mask:0xf bank_mask:0xc
	v_mov_b32_dpp v37, v249 quad_perm:[0,1,2,3] row_mask:0xf bank_mask:0xc
	v_mov_b32_dpp v38, v250 quad_perm:[0,1,2,3] row_mask:0xf bank_mask:0xc
	v_mov_b32_dpp v39, v251 quad_perm:[0,1,2,3] row_mask:0xf bank_mask:0xc
	s_waitcnt vmcnt(18)
	v_pk_add_f32 v[36:37], v[36:37], v[168:169]
	v_pk_add_f32 v[38:39], v[38:39], v[170:171]
	v_pk_add_f32 v[28:29], v[28:29], v[172:173]
	v_pk_add_f32 v[30:31], v[30:31], v[174:175]
	global_store_dwordx4 v238, v[36:39], s[48:49] nt
	global_store_dwordx4 v246, v[28:31], s[48:49] nt
	v_mov_b32_dpp v248, v8 row_ror:8 row_mask:0xf bank_mask:0xf
	v_mov_b32_dpp v249, v9 row_ror:8 row_mask:0xf bank_mask:0xf
	v_mov_b32_dpp v250, v10 row_ror:8 row_mask:0xf bank_mask:0xf
	v_mov_b32_dpp v251, v11 row_ror:8 row_mask:0xf bank_mask:0xf
	v_mov_b32_dpp v8, v16 row_ror:8 row_mask:0xf bank_mask:0x3
	v_mov_b32_dpp v9, v17 row_ror:8 row_mask:0xf bank_mask:0x3
	v_mov_b32_dpp v10, v18 row_ror:8 row_mask:0xf bank_mask:0x3
	v_mov_b32_dpp v11, v19 row_ror:8 row_mask:0xf bank_mask:0x3
	v_mov_b32_dpp v16, v248 quad_perm:[0,1,2,3] row_mask:0xf bank_mask:0xc
	v_mov_b32_dpp v17, v249 quad_perm:[0,1,2,3] row_mask:0xf bank_mask:0xc
	v_mov_b32_dpp v18, v250 quad_perm:[0,1,2,3] row_mask:0xf bank_mask:0xc
	v_mov_b32_dpp v19, v251 quad_perm:[0,1,2,3] row_mask:0xf bank_mask:0xc
	s_waitcnt vmcnt(18)
	v_pk_add_f32 v[16:17], v[16:17], v[176:177]
	v_pk_add_f32 v[18:19], v[18:19], v[178:179]
	v_pk_add_f32 v[8:9], v[8:9], v[180:181]
	v_pk_add_f32 v[10:11], v[10:11], v[182:183]
	global_store_dwordx4 v238, v[16:19], s[48:49] offset:512 nt
	global_store_dwordx4 v246, v[8:11], s[48:49] offset:512 nt
	v_mov_b32_dpp v248, v12 row_ror:8 row_mask:0xf bank_mask:0xf
	v_mov_b32_dpp v249, v13 row_ror:8 row_mask:0xf bank_mask:0xf
	v_mov_b32_dpp v250, v14 row_ror:8 row_mask:0xf bank_mask:0xf
	v_mov_b32_dpp v251, v15 row_ror:8 row_mask:0xf bank_mask:0xf
	v_mov_b32_dpp v12, v20 row_ror:8 row_mask:0xf bank_mask:0x3
	v_mov_b32_dpp v13, v21 row_ror:8 row_mask:0xf bank_mask:0x3
	v_mov_b32_dpp v14, v22 row_ror:8 row_mask:0xf bank_mask:0x3
	v_mov_b32_dpp v15, v23 row_ror:8 row_mask:0xf bank_mask:0x3
	v_mov_b32_dpp v20, v248 quad_perm:[0,1,2,3] row_mask:0xf bank_mask:0xc
	v_mov_b32_dpp v21, v249 quad_perm:[0,1,2,3] row_mask:0xf bank_mask:0xc
	v_mov_b32_dpp v22, v250 quad_perm:[0,1,2,3] row_mask:0xf bank_mask:0xc
	v_mov_b32_dpp v23, v251 quad_perm:[0,1,2,3] row_mask:0xf bank_mask:0xc
	s_waitcnt vmcnt(18)
	v_pk_add_f32 v[20:21], v[20:21], v[184:185]
	v_pk_add_f32 v[22:23], v[22:23], v[186:187]
	v_pk_add_f32 v[12:13], v[12:13], v[188:189]
	v_pk_add_f32 v[14:15], v[14:15], v[190:191]
	global_store_dwordx4 v239, v[20:23], s[48:49] nt
	global_store_dwordx4 v247, v[12:15], s[48:49] nt
	v_mov_b32_dpp v248, v0 row_ror:8 row_mask:0xf bank_mask:0xf
	v_mov_b32_dpp v249, v1 row_ror:8 row_mask:0xf bank_mask:0xf
	v_mov_b32_dpp v250, v2 row_ror:8 row_mask:0xf bank_mask:0xf
	v_mov_b32_dpp v251, v3 row_ror:8 row_mask:0xf bank_mask:0xf
	v_mov_b32_dpp v0, v4 row_ror:8 row_mask:0xf bank_mask:0x3
	v_mov_b32_dpp v1, v5 row_ror:8 row_mask:0xf bank_mask:0x3
	v_mov_b32_dpp v2, v6 row_ror:8 row_mask:0xf bank_mask:0x3
	v_mov_b32_dpp v3, v7 row_ror:8 row_mask:0xf bank_mask:0x3
	v_mov_b32_dpp v4, v248 quad_perm:[0,1,2,3] row_mask:0xf bank_mask:0xc
	v_mov_b32_dpp v5, v249 quad_perm:[0,1,2,3] row_mask:0xf bank_mask:0xc
	v_mov_b32_dpp v6, v250 quad_perm:[0,1,2,3] row_mask:0xf bank_mask:0xc
	v_mov_b32_dpp v7, v251 quad_perm:[0,1,2,3] row_mask:0xf bank_mask:0xc
	s_waitcnt vmcnt(18)
	v_pk_add_f32 v[4:5], v[4:5], v[192:193]
	v_pk_add_f32 v[6:7], v[6:7], v[194:195]
	v_pk_add_f32 v[0:1], v[0:1], v[196:197]
	v_pk_add_f32 v[2:3], v[2:3], v[198:199]
	global_store_dwordx4 v239, v[4:7], s[48:49] offset:512 nt
	global_store_dwordx4 v247, v[0:3], s[48:49] offset:512 nt
	s_cbranch_vccnz .LBB0_985
	s_andn2_b64 vcc, exec, s[4:5]
	s_cbranch_vccnz .LBB0_984
	s_barrier
	s_branch .LBB0_984
